# speedup vs baseline: 1.0173x; 1.0043x over previous
; __device__ __forceinline__ void dil_wave_item(const bf16* __restrict__ qkv, bf16* __restrict__ odil, float* __restrict__ lse,
;                               int pat, int g  , int head, char* wl  , const int W) {
;     ...
;   const int dil = (pat == 0) ? 1 : (pat == 1 ? 4 : 16);
;   int seq0, slen, gl;
;   if (g < 256) { seq0 = 0; slen = 8192; gl = g; } else if (g < 512) { seq0 = 8192; slen = 8192; gl = g - 256; } else { seq0 = 16384; slen = 16384; gl = g - 512; }
;   const int L = slen / dil, tpr = L / 32, res = gl / tpr, i0 = (gl % tpr) * 32;
; __device__ __forceinline__ void attention_phase(const Params& p, int layer, const int W) {
;     ...
;   for (int rep = 0; rep < REP_DIL; ++rep)
;   for (int it = blockIdx.x; it < 3 * 1024; it += gridDim.x) {
;     dil_wave_item(qkv, odil, lse, it / 1024, it % 1024, wid, lds + wid * 4096, W);
.LBB0_83:
	s_and_b32 s98, s70, 0xfffffc00
	s_and_b32 s99, s70, 7
	s_lshl_b32 s99, s99, 7
	s_or_b32 s98, s98, s99
	s_bfe_u32 s99, s70, 0x20008
	s_lshl_b32 s99, s99, 5
	s_or_b32 s98, s98, s99
	s_bfe_u32 s99, s70, 0x50003
	s_or_b32 s98, s98, s99
	s_ashr_i32 s4, s98, 31
	s_lshr_b32 s4, s4, 22
	s_add_i32 s4, s98, s4
	s_ashr_i32 s10, s4, 10
	s_and_b32 s4, s4, 0xfffffc00
	s_sub_i32 s6, s98, s4
	s_cmpk_lt_i32 s6, 0x100
	v_mbcnt_lo_u32_b32 v92, -1, 0
	v_mbcnt_hi_u32_b32 v92, -1, v92
	s_cbranch_scc1 .LBB0_89
	s_lshl_b32 s4, s10, 10
	s_sub_i32 s7, s98, s4
	s_cmpk_gt_u32 s6, 0x1ff
	s_mov_b64 s[4:5], -1
	s_cbranch_scc0 .LBB0_86
	s_add_i32 s6, s7, 0xfffffe00
	s_mov_b64 s[4:5], 0

; __device__ __forceinline__ void dil_wave_item(const bf16* __restrict__ qkv, bf16* __restrict__ odil, float* __restrict__ lse,
;                               int pat, int g  , int head, char* wl  , const int W) {
;     ...
;   const int dil = (pat == 0) ? 1 : (pat == 1 ? 4 : 16);
;   int seq0, slen, gl;
;   if (g < 256) { seq0 = 0; slen = 8192; gl = g; } else if (g < 512) { seq0 = 8192; slen = 8192; gl = g - 256; } else { seq0 = 16384; slen = 16384; gl = g - 512; }
;   const int L = slen / dil, tpr = L / 32, res = gl / tpr, i0 = (gl % tpr) * 32;
;   const int tbase = seq0 + res;
;   bf16x8 qr[4];
;   { const bf16* qp = qkv + (size_t)(tbase + (i0 + r32) * dil) * LDQ + 1536 + head * 64 + hi * 8;
; #pragma unroll
;     for (int d0 = 0; d0 < 4; ++d0) qr[d0] = *reinterpret_cast<const bf16x8*>(qp + d0 * 16); }
;   f32x16 sc[5];
; #pragma unroll
;   for (int kb = 0; kb < 5; ++kb) {
;     int kc = i0 - 64 + kb * 32 + r32; kc = min(max(kc, 0), L - 1);
;     const bf16* kp = qkv + (size_t)(tbase + kc * dil) * LDQ + 2048 + head * 64 + hi * 8;
;     f32x16 a = {};
; #pragma unroll
;     for (int d0 = 0; d0 < 4; ++d0) {
;       bf16x8 kf = *reinterpret_cast<const bf16x8*>(kp + d0 * 16);
;       a = __builtin_amdgcn_mfma_f32_32x32x16_bf16(kf, qr[d0], a, 0, 0, 0);
;     }
;     sc[kb] = a;
;   }
.LBB0_90:
	s_add_i32 s7, s98, 0x3ff
	s_and_b32 s11, s98, 0xfffffc00
	s_cmpk_eq_i32 s11, 0x400
	s_cselect_b32 s11, 2, 4
	s_cmpk_gt_u32 s7, 0x7fe
	s_cselect_b32 s71, s11, 0
	s_lshr_b32 s7, s5, s71
	s_lshr_b32 s5, s7, 5
	s_sext_i32_i16 s11, s5
	v_cvt_f32_i32_e32 v0, s11
	s_sext_i32_i16 s66, s6
	v_cvt_f32_i32_e32 v1, s66
	s_xor_b32 s11, s66, s11
	v_rcp_iflag_f32_e32 v2, v0
	s_ashr_i32 s11, s11, 30
	s_or_b32 s11, s11, 1
	v_and_b32_e32 v91, 31, v92
	v_mul_f32_e32 v2, v1, v2
	v_trunc_f32_e32 v2, v2
	v_fma_f32 v1, -v2, v0, v1
	v_cvt_i32_f32_e32 v2, v2
	v_cmp_ge_f32_e64 s[66:67], |v1|, |v0|
	s_and_b64 s[66:67], s[66:67], exec
	s_cselect_b32 s11, s11, 0
	v_readfirstlane_b32 s66, v2
	s_add_i32 s11, s66, s11
	s_sext_i32_i16 s66, s11
	s_mul_i32 s11, s11, s5
	s_sub_i32 s5, s6, s11
	s_sext_i32_i16 s5, s5
	s_lshl_b32 s78, s5, 5
	v_or_b32_e32 v134, s78, v91
	v_subrev_u32_e32 v87, 64, v134
	s_add_i32 s6, s7, -1
	v_max_i32_e32 v4, 0, v87
	v_min_u32_e32 v4, s6, v4
	s_add_i32 s79, s4, s66
	v_lshlrev_b32_e32 v4, s71, v4
	v_add_u32_e32 v4, s79, v4
	v_bfe_u32 v90, v92, 5, 1
	v_mad_i64_i32 v[4:5], s[4:5], v4, s62, v[84:85]
	v_lshlrev_b32_e32 v82, 4, v90
	v_lshl_add_u64 v[4:5], v[4:5], 0, s[74:75]
	v_lshl_add_u64 v[20:21], v[4:5], 0, v[82:83]
	v_max_i32_e32 v8, 0xffffffe0, v87
	v_add_co_u32_e32 v4, vcc, s63, v20
	v_add_u32_e32 v8, 32, v8
	s_nop 0
	v_addc_co_u32_e32 v5, vcc, 0, v21, vcc
	v_min_u32_e32 v8, s6, v8
	v_lshlrev_b32_e32 v86, s71, v134
	global_load_dwordx4 v[4:7], v[4:5], off
	v_lshlrev_b32_e32 v8, s71, v8
	v_add_u32_e32 v0, s79, v86
	v_add_u32_e32 v8, s79, v8
	v_mad_i64_i32 v[0:1], s[4:5], v0, s62, v[80:81]
	v_mad_i64_i32 v[8:9], s[4:5], v8, s62, v[84:85]
	v_lshl_add_u64 v[126:127], v[0:1], 0, v[82:83]
	v_lshl_add_u64 v[8:9], v[8:9], 0, s[74:75]
	global_load_dwordx4 v[0:3], v[126:127], off offset:3072
	v_lshl_add_u64 v[22:23], v[8:9], 0, v[82:83]
	v_add_co_u32_e32 v8, vcc, s63, v22
	v_max_i32_e32 v12, 0xffffffc0, v87
	s_nop 0
	v_addc_co_u32_e32 v9, vcc, 0, v23, vcc
	global_load_dwordx4 v[8:11], v[8:9], off
	v_add_u32_e32 v12, 64, v12
	v_min_u32_e32 v12, s6, v12
	s_waitcnt vmcnt(11)
	v_max_i32_e32 v16, 0xffffffa0, v87
	v_lshlrev_b32_e32 v12, s71, v12
	v_add_u32_e32 v16, 0x60, v16
	v_add_u32_e32 v12, s79, v12
	v_min_u32_e32 v16, s6, v16
	v_mad_i64_i32 v[12:13], s[4:5], v12, s62, v[84:85]
	v_lshlrev_b32_e32 v16, s71, v16
	v_lshl_add_u64 v[12:13], v[12:13], 0, s[74:75]
	v_add_u32_e32 v16, s79, v16
	v_lshl_add_u64 v[24:25], v[12:13], 0, v[82:83]
	v_mad_i64_i32 v[16:17], s[4:5], v16, s62, v[84:85]
	v_add_co_u32_e32 v12, vcc, s63, v24
	v_lshl_add_u64 v[16:17], v[16:17], 0, s[74:75]
	s_nop 0
	v_addc_co_u32_e32 v13, vcc, 0, v25, vcc
	v_lshl_add_u64 v[26:27], v[16:17], 0, v[82:83]
	v_add_co_u32_e32 v16, vcc, s63, v26
	global_load_dwordx4 v[12:15], v[12:13], off
	s_nop 0
	v_addc_co_u32_e32 v17, vcc, 0, v27, vcc
	v_lshl_add_u64 v[118:119], v[20:21], 0, s[8:9]
	v_lshl_add_u64 v[128:129], v[22:23], 0, s[8:9]
	global_load_dwordx4 v[16:19], v[16:17], off
	s_nop 0
	global_load_dwordx4 v[94:97], v[118:119], off offset:32
	global_load_dwordx4 v[98:101], v[126:127], off offset:3104
	global_load_dwordx4 v[102:105], v[118:119], off offset:96
	v_lshl_add_u64 v[130:131], v[24:25], 0, s[8:9]
	v_lshl_add_u64 v[132:133], v[26:27], 0, s[8:9]
	v_lshlrev_b32_e32 v90, 2, v90
	v_sub_u32_e32 v93, v90, v91
	s_waitcnt vmcnt(6)
	v_mfma_f32_32x32x16_bf16 v[64:79], v[4:7], v[0:3], 0
	global_load_dwordx4 v[4:7], v[128:129], off offset:32
	global_load_dwordx4 v[106:109], v[128:129], off offset:96
	global_load_dwordx4 v[110:113], v[130:131], off offset:96
	s_waitcnt vmcnt(8)
	v_mfma_f32_32x32x16_bf16 v[48:63], v[8:11], v[0:3], 0
	global_load_dwordx4 v[8:11], v[130:131], off offset:32
	s_waitcnt vmcnt(8)
	v_mfma_f32_32x32x16_bf16 v[32:47], v[12:15], v[0:3], 0
	global_load_dwordx4 v[12:15], v[132:133], off offset:32
	global_load_dwordx4 v[114:117], v[132:133], off offset:96
	s_nop 0
	global_load_dwordx4 v[118:121], v[118:119], off offset:64
	s_nop 0
	global_load_dwordx4 v[122:125], v[126:127], off offset:3136
	s_waitcnt vmcnt(9)
	v_mfma_f32_32x32x16_bf16 v[64:79], v[94:97], v[98:101], v[64:79]
	global_load_dwordx4 v[94:97], v[128:129], off offset:64
	v_mfma_f32_32x32x16_bf16 v[16:31], v[16:19], v[0:3], 0
	s_waitcnt vmcnt(4)
	v_mfma_f32_32x32x16_bf16 v[16:31], v[12:15], v[98:101], v[16:31]
	v_mfma_f32_32x32x16_bf16 v[48:63], v[4:7], v[98:101], v[48:63]
	global_load_dwordx4 v[4:7], v[130:131], off offset:64
	s_nop 0
	global_load_dwordx4 v[126:129], v[126:127], off offset:3168
	v_mfma_f32_32x32x16_bf16 v[32:47], v[8:11], v[98:101], v[32:47]
	global_load_dwordx4 v[8:11], v[132:133], off offset:64
	s_waitcnt vmcnt(3)
	v_mfma_f32_32x32x16_bf16 v[48:63], v[94:97], v[122:125], v[48:63]
	s_waitcnt vmcnt(2)
	v_mfma_f32_32x32x16_bf16 v[32:47], v[4:7], v[122:125], v[32:47]
	v_max_i32_e32 v4, 0xffffff80, v87
	v_add_u32_e32 v4, 0x80, v4
	v_min_u32_e32 v4, s6, v4
	v_lshlrev_b32_e32 v4, s71, v4
	v_add_u32_e32 v4, s79, v4
	v_mad_i64_i32 v[4:5], s[4:5], v4, s62, v[84:85]
	v_lshl_add_u64 v[4:5], v[4:5], 0, s[74:75]
	s_waitcnt vmcnt(0)
	v_mfma_f32_32x32x16_bf16 v[16:31], v[8:11], v[122:125], v[16:31]
	v_lshl_add_u64 v[8:9], v[4:5], 0, v[82:83]
	v_add_co_u32_e32 v4, vcc, s63, v8
	v_and_b32_e32 v87, 63, v92
	s_nop 0
	v_addc_co_u32_e32 v5, vcc, 0, v9, vcc
	global_load_dwordx4 v[4:7], v[4:5], off
	v_mfma_f32_32x32x16_bf16 v[64:79], v[118:121], v[122:125], v[64:79]
	v_cmp_gt_u32_e32 vcc, s64, v93
	v_mfma_f32_32x32x16_bf16 v[48:63], v[106:109], v[126:129], v[48:63]
	v_lshl_add_u64 v[106:107], v[8:9], 0, s[8:9]
	v_mfma_f32_32x32x16_bf16 v[64:79], v[102:105], v[126:129], v[64:79]
	global_load_dwordx4 v[94:97], v[106:107], off offset:32
	global_load_dwordx4 v[102:105], v[106:107], off offset:96
	s_nop 7
	v_mul_f32_e32 v48, 0x3e38aa3b, v48
	global_load_dwordx4 v[106:109], v[106:107], off offset:64
	v_mul_f32_e32 v49, 0x3e38aa3b, v49
	v_mul_f32_e32 v50, 0x3e38aa3b, v50
	v_mul_f32_e32 v51, 0x3e38aa3b, v51
	v_mul_f32_e32 v52, 0x3e38aa3b, v52
	s_waitcnt vmcnt(3)
; __device__ __forceinline__ int crow(int r, int hi) { return (r & 3) + 8 * (r >> 2) + 4 * hi; }
; __device__ __forceinline__ void dil_wave_item(const bf16* __restrict__ qkv, bf16* __restrict__ odil, float* __restrict__ lse,
;                               int pat, int g  , int head, char* wl  , const int W) {
;     ...
;   for (int kb = 0; kb < 5; ++kb) {
;     int kc = i0 - 64 + kb * 32 + r32; kc = min(max(kc, 0), L - 1);
;     const bf16* kp = qkv + (size_t)(tbase + kc * dil) * LDQ + 2048 + head * 64 + hi * 8;
;     f32x16 a = {};
; #pragma unroll
;     for (int d0 = 0; d0 < 4; ++d0) {
;       bf16x8 kf = *reinterpret_cast<const bf16x8*>(kp + d0 * 16);
;       a = __builtin_amdgcn_mfma_f32_32x32x16_bf16(kf, qr[d0], a, 0, 0, 0);
;     }
;     sc[kb] = a;
;   }
;   float mx = -1e30f;
; #pragma unroll
;   for (int kb = 0; kb < 5; ++kb)
; #pragma unroll
;     for (int r = 0; r < 16; ++r) {
;       const int rel = kb * 32 - 64 + crow(r, hi) - r32;
;       const int kc = i0 + r32 + rel;
;       const bool ok = (rel >= -64) && (rel <= 64) && (kc >= 0) && (kc < L);
;       const float s = ok ? sc[kb][r] * AC : -1e30f;
;       sc[kb][r] = s; mx = fmaxf(mx, s);
;     }
;     ...
;     for (int i = 0; i < 4; ++i) {
;       const int key = i * 8 + (lane >> 3);
;       int kc = i0 - 64 + kb * 32 + key; kc = min(max(kc, 0), L - 1);
;       vr[i] = *reinterpret_cast<const bf16x8*>(qkv + (size_t)(tbase + kc * dil) * LDQ + 2560 + head * 64 + (lane & 7) * 8);
	v_mfma_f32_32x32x16_bf16 v[0:15], v[4:7], v[0:3], 0
	v_mul_f32_e32 v64, 0x3e38aa3b, v64
	v_mul_f32_e32 v65, 0x3e38aa3b, v65
	v_mul_f32_e32 v66, 0x3e38aa3b, v66
	v_mul_f32_e32 v67, 0x3e38aa3b, v67
	v_mul_f32_e32 v68, 0x3e38aa3b, v68
	v_mul_f32_e32 v69, 0x3e38aa3b, v69
	v_mul_f32_e32 v70, 0x3e38aa3b, v70
	s_waitcnt vmcnt(2)
	v_mfma_f32_32x32x16_bf16 v[0:15], v[94:97], v[98:101], v[0:15]
	v_add_u32_e32 v94, v134, v93
	v_subrev_u32_e32 v95, 64, v94
	v_cmp_gt_u32_e64 s[4:5], s7, v95
	s_and_b64 vcc, vcc, s[4:5]
	v_subrev_u32_e32 v95, 63, v94
	v_add_u32_e32 v96, 1, v93
	v_cndmask_b32_e32 v64, v89, v64, vcc
	v_cmp_gt_u32_e32 vcc, s64, v96
	v_cmp_gt_u32_e64 s[4:5], s7, v95
	s_waitcnt vmcnt(0)
	v_mfma_f32_32x32x16_bf16 v[0:15], v[106:109], v[122:125], v[0:15]
	v_bfe_u32 v232, v92, 3, 3
	v_and_b32_e32 v233, 7, v92
	v_add_u32_e32 v232, s78, v232
	v_lshlrev_b32_e32 v233, 4, v233
	v_add_u32_e32 v233, s74, v233
	v_add_u32_e32 v233, 0x1400, v233
	v_add_u32_e32 v234, 0xffffffc0, v232
	v_max_i32_e32 v234, 0, v234
	v_min_u32_e32 v234, s6, v234
	v_lshlrev_b32_e32 v234, s71, v234
	v_add_u32_e32 v234, s79, v234
	v_mad_u32_u24 v234, v234, s62, v233
	global_load_dwordx4 v[152:155], v234, s[36:37]
	v_add_u32_e32 v235, 0xffffffc8, v232
	v_max_i32_e32 v235, 0, v235
	v_min_u32_e32 v235, s6, v235
	v_lshlrev_b32_e32 v235, s71, v235
	v_add_u32_e32 v235, s79, v235
	v_mad_u32_u24 v235, v235, s62, v233
	global_load_dwordx4 v[156:159], v235, s[36:37]
	v_add_u32_e32 v234, 0xffffffd0, v232
	v_max_i32_e32 v234, 0, v234
	v_min_u32_e32 v234, s6, v234
	v_lshlrev_b32_e32 v234, s71, v234
	v_add_u32_e32 v234, s79, v234
	v_mad_u32_u24 v234, v234, s62, v233
	global_load_dwordx4 v[160:163], v234, s[36:37]
	v_add_u32_e32 v235, 0xffffffd8, v232
	v_max_i32_e32 v235, 0, v235
	v_min_u32_e32 v235, s6, v235
	v_lshlrev_b32_e32 v235, s71, v235
	v_add_u32_e32 v235, s79, v235
	v_mad_u32_u24 v235, v235, s62, v233
	global_load_dwordx4 v[164:167], v235, s[36:37]
	v_add_u32_e32 v234, 0xffffffe0, v232
	v_max_i32_e32 v234, 0, v234
	v_min_u32_e32 v234, s6, v234
	v_lshlrev_b32_e32 v234, s71, v234
	v_add_u32_e32 v234, s79, v234
	v_mad_u32_u24 v234, v234, s62, v233
	global_load_dwordx4 v[168:171], v234, s[36:37]
	v_add_u32_e32 v235, 0xffffffe8, v232
	v_max_i32_e32 v235, 0, v235
	v_min_u32_e32 v235, s6, v235
	v_lshlrev_b32_e32 v235, s71, v235
	v_add_u32_e32 v235, s79, v235
	v_mad_u32_u24 v235, v235, s62, v233
	global_load_dwordx4 v[172:175], v235, s[36:37]
	v_add_u32_e32 v234, -16, v232
	v_max_i32_e32 v234, 0, v234
	v_min_u32_e32 v234, s6, v234
	v_lshlrev_b32_e32 v234, s71, v234
	v_add_u32_e32 v234, s79, v234
	v_mad_u32_u24 v234, v234, s62, v233
	global_load_dwordx4 v[176:179], v234, s[36:37]
	v_add_u32_e32 v235, -8, v232
	v_max_i32_e32 v235, 0, v235
	v_min_u32_e32 v235, s6, v235
	v_lshlrev_b32_e32 v235, s71, v235
	v_add_u32_e32 v235, s79, v235
	v_mad_u32_u24 v235, v235, s62, v233
	global_load_dwordx4 v[180:183], v235, s[36:37]
	v_add_u32_e32 v234, 0, v232
	v_max_i32_e32 v234, 0, v234
	v_min_u32_e32 v234, s6, v234
	v_lshlrev_b32_e32 v234, s71, v234
	v_add_u32_e32 v234, s79, v234
	v_mad_u32_u24 v234, v234, s62, v233
	global_load_dwordx4 v[184:187], v234, s[36:37]
	v_add_u32_e32 v235, 8, v232
	v_max_i32_e32 v235, 0, v235
	v_min_u32_e32 v235, s6, v235
	v_lshlrev_b32_e32 v235, s71, v235
	v_add_u32_e32 v235, s79, v235
	v_mad_u32_u24 v235, v235, s62, v233
	global_load_dwordx4 v[188:191], v235, s[36:37]
	v_add_u32_e32 v234, 16, v232
	v_max_i32_e32 v234, 0, v234
	v_min_u32_e32 v234, s6, v234
	v_lshlrev_b32_e32 v234, s71, v234
	v_add_u32_e32 v234, s79, v234
	v_mad_u32_u24 v234, v234, s62, v233
	global_load_dwordx4 v[192:195], v234, s[36:37]
	v_add_u32_e32 v235, 24, v232
	v_max_i32_e32 v235, 0, v235
	v_min_u32_e32 v235, s6, v235
	v_lshlrev_b32_e32 v235, s71, v235
	v_add_u32_e32 v235, s79, v235
	v_mad_u32_u24 v235, v235, s62, v233
	global_load_dwordx4 v[196:199], v235, s[36:37]
	v_add_u32_e32 v234, 32, v232
	v_max_i32_e32 v234, 0, v234
	v_min_u32_e32 v234, s6, v234
	v_lshlrev_b32_e32 v234, s71, v234
	v_add_u32_e32 v234, s79, v234
	v_mad_u32_u24 v234, v234, s62, v233
	global_load_dwordx4 v[200:203], v234, s[36:37]
	v_add_u32_e32 v235, 40, v232
	v_max_i32_e32 v235, 0, v235
	v_min_u32_e32 v235, s6, v235
	v_lshlrev_b32_e32 v235, s71, v235
	v_add_u32_e32 v235, s79, v235
	v_mad_u32_u24 v235, v235, s62, v233
	global_load_dwordx4 v[204:207], v235, s[36:37]
	v_add_u32_e32 v234, 48, v232
	v_max_i32_e32 v234, 0, v234
	v_min_u32_e32 v234, s6, v234
	v_lshlrev_b32_e32 v234, s71, v234
	v_add_u32_e32 v234, s79, v234
	v_mad_u32_u24 v234, v234, s62, v233
	global_load_dwordx4 v[208:211], v234, s[36:37]
	v_add_u32_e32 v235, 56, v232
	v_max_i32_e32 v235, 0, v235
	v_min_u32_e32 v235, s6, v235
	v_lshlrev_b32_e32 v235, s71, v235
	v_add_u32_e32 v235, s79, v235
	v_mad_u32_u24 v235, v235, s62, v233
	global_load_dwordx4 v[212:215], v235, s[36:37]
	v_add_u32_e32 v234, 64, v232
	v_max_i32_e32 v234, 0, v234
	v_min_u32_e32 v234, s6, v234
	v_lshlrev_b32_e32 v234, s71, v234
	v_add_u32_e32 v234, s79, v234
	v_mad_u32_u24 v234, v234, s62, v233
	global_load_dwordx4 v[216:219], v234, s[36:37]
	v_add_u32_e32 v235, 0x00000048, v232
	v_max_i32_e32 v235, 0, v235
	v_min_u32_e32 v235, s6, v235
	v_lshlrev_b32_e32 v235, s71, v235
	v_add_u32_e32 v235, s79, v235
	v_mad_u32_u24 v235, v235, s62, v233
	global_load_dwordx4 v[220:223], v235, s[36:37]
	v_add_u32_e32 v234, 0x00000050, v232
	v_max_i32_e32 v234, 0, v234
	v_min_u32_e32 v234, s6, v234
	v_lshlrev_b32_e32 v234, s71, v234
	v_add_u32_e32 v234, s79, v234
	v_mad_u32_u24 v234, v234, s62, v233
	global_load_dwordx4 v[224:227], v234, s[36:37]
	v_add_u32_e32 v235, 0x00000058, v232
	v_max_i32_e32 v235, 0, v235
; __device__ __forceinline__ int crow(int r, int hi) { return (r & 3) + 8 * (r >> 2) + 4 * hi; }
; __device__ __forceinline__ void dil_wave_item(const bf16* __restrict__ qkv, bf16* __restrict__ odil, float* __restrict__ lse,
;                               int pat, int g  , int head, char* wl  , const int W) {
;     ...
;   float mx = -1e30f;
; #pragma unroll
;   for (int kb = 0; kb < 5; ++kb)
; #pragma unroll
;     for (int r = 0; r < 16; ++r) {
;       const int rel = kb * 32 - 64 + crow(r, hi) - r32;
;       const int kc = i0 + r32 + rel;
;       const bool ok = (rel >= -64) && (rel <= 64) && (kc >= 0) && (kc < L);
;       const float s = ok ? sc[kb][r] * AC : -1e30f;
;       sc[kb][r] = s; mx = fmaxf(mx, s);
;     }
	v_min_u32_e32 v235, s6, v235
	v_lshlrev_b32_e32 v235, s71, v235
	v_add_u32_e32 v235, s79, v235
	v_mad_u32_u24 v235, v235, s62, v233
	global_load_dwordx4 v[228:231], v235, s[36:37]
	s_and_b64 vcc, vcc, s[4:5]
	v_subrev_u32_e32 v97, 62, v94
	v_add_u32_e32 v98, 2, v93
	v_cndmask_b32_e32 v65, v89, v65, vcc
	v_cmp_gt_u32_e32 vcc, s64, v98
	v_cmp_gt_u32_e64 s[4:5], s7, v97
	s_and_b64 vcc, vcc, s[4:5]
	v_subrev_u32_e32 v97, 61, v94
	v_add_u32_e32 v99, 3, v93
	v_cndmask_b32_e32 v66, v89, v66, vcc
	v_cmp_gt_u32_e32 vcc, s64, v99
	v_cmp_gt_u32_e64 s[4:5], s7, v97
	s_and_b64 vcc, vcc, s[4:5]
	v_subrev_u32_e32 v97, 56, v94
	v_add_u32_e32 v100, 8, v93
	v_cndmask_b32_e32 v67, v89, v67, vcc
	v_cmp_gt_u32_e32 vcc, s64, v100
	v_cmp_gt_u32_e64 s[4:5], s7, v97
	s_and_b64 vcc, vcc, s[4:5]
	v_subrev_u32_e32 v97, 55, v94
	v_add_u32_e32 v101, 9, v93
	v_cndmask_b32_e32 v68, v89, v68, vcc
	v_cmp_gt_u32_e32 vcc, s64, v101
	v_cmp_gt_u32_e64 s[4:5], s7, v97
	v_mfma_f32_32x32x16_bf16 v[0:15], v[102:105], v[126:129], v[0:15]
	s_and_b64 vcc, vcc, s[4:5]
	v_subrev_u32_e32 v97, 54, v94
	v_add_u32_e32 v102, 10, v93
	v_cndmask_b32_e32 v69, v89, v69, vcc
	v_cmp_gt_u32_e32 vcc, s64, v102
	v_cmp_gt_u32_e64 s[4:5], s7, v97
	s_and_b64 vcc, vcc, s[4:5]
	v_subrev_u32_e32 v97, 53, v94
	v_add_u32_e32 v103, 11, v93
	v_cndmask_b32_e32 v70, v89, v70, vcc
	v_cmp_gt_u32_e32 vcc, s64, v103
	v_cmp_gt_u32_e64 s[4:5], s7, v97
	v_mul_f32_e32 v71, 0x3e38aa3b, v71
	s_and_b64 vcc, vcc, s[4:5]
	v_subrev_u32_e32 v97, 48, v94
	v_add_u32_e32 v104, 16, v93
	v_cndmask_b32_e32 v71, v89, v71, vcc
	v_cmp_gt_u32_e32 vcc, s64, v104
	v_cmp_gt_u32_e64 s[4:5], s7, v97
	v_mul_f32_e32 v72, 0x3e38aa3b, v72
	s_and_b64 vcc, vcc, s[4:5]
	v_subrev_u32_e32 v97, 47, v94
	v_add_u32_e32 v105, 17, v93
	v_cndmask_b32_e32 v72, v89, v72, vcc
	v_cmp_gt_u32_e32 vcc, s64, v105
	v_cmp_gt_u32_e64 s[4:5], s7, v97
	v_mul_f32_e32 v73, 0x3e38aa3b, v73
	s_and_b64 vcc, vcc, s[4:5]
	v_subrev_u32_e32 v97, 46, v94
	v_add_u32_e32 v106, 18, v93
	v_cndmask_b32_e32 v73, v89, v73, vcc
	v_cmp_gt_u32_e32 vcc, s64, v106
	v_cmp_gt_u32_e64 s[4:5], s7, v97
	v_mul_f32_e32 v74, 0x3e38aa3b, v74
	s_and_b64 vcc, vcc, s[4:5]
	v_subrev_u32_e32 v97, 45, v94
	v_add_u32_e32 v107, 19, v93
	v_cndmask_b32_e32 v74, v89, v74, vcc
	v_cmp_gt_u32_e32 vcc, s64, v107
	v_cmp_gt_u32_e64 s[4:5], s7, v97
	v_mul_f32_e32 v75, 0x3e38aa3b, v75
	s_and_b64 vcc, vcc, s[4:5]
	v_subrev_u32_e32 v97, 40, v94
	v_add_u32_e32 v108, 24, v93
	v_cndmask_b32_e32 v75, v89, v75, vcc
	v_cmp_gt_u32_e32 vcc, s64, v108
	v_cmp_gt_u32_e64 s[4:5], s7, v97
	v_mul_f32_e32 v76, 0x3e38aa3b, v76
	s_and_b64 vcc, vcc, s[4:5]
	v_subrev_u32_e32 v97, 39, v94
	v_add_u32_e32 v109, 25, v93
	v_cndmask_b32_e32 v76, v89, v76, vcc
	v_cmp_gt_u32_e32 vcc, s64, v109
	v_cmp_gt_u32_e64 s[4:5], s7, v97
	v_mfma_f32_32x32x16_bf16 v[32:47], v[110:113], v[126:129], v[32:47]
	v_mul_f32_e32 v77, 0x3e38aa3b, v77
	s_and_b64 vcc, vcc, s[4:5]
	v_subrev_u32_e32 v97, 38, v94
	v_add_u32_e32 v110, 26, v93
	v_cndmask_b32_e32 v77, v89, v77, vcc
	v_cmp_gt_u32_e32 vcc, s64, v110
	v_cmp_gt_u32_e64 s[4:5], s7, v97
	v_mul_f32_e32 v78, 0x3e38aa3b, v78
	s_and_b64 vcc, vcc, s[4:5]
	v_subrev_u32_e32 v97, 37, v94
	v_add_u32_e32 v111, 27, v93
	v_cndmask_b32_e32 v78, v89, v78, vcc
	v_cmp_gt_u32_e32 vcc, s64, v111
	v_cmp_gt_u32_e64 s[4:5], s7, v97
	v_mul_f32_e32 v79, 0x3e38aa3b, v79
	s_and_b64 vcc, vcc, s[4:5]
	v_subrev_u32_e32 v97, 32, v94
	v_cndmask_b32_e32 v79, v89, v79, vcc
	v_cmp_gt_u32_e32 vcc, s7, v97
	v_subrev_u32_e32 v97, 31, v94
	v_max3_f32 v95, v64, s65, v65
	v_cndmask_b32_e32 v48, v89, v48, vcc
	v_cmp_gt_u32_e32 vcc, s7, v97
	v_subrev_u32_e32 v97, 30, v94
	v_mul_f32_e32 v53, 0x3e38aa3b, v53
	v_cndmask_b32_e32 v49, v89, v49, vcc
	v_cmp_gt_u32_e32 vcc, s7, v97
	v_subrev_u32_e32 v97, 29, v94
	v_max3_f32 v95, v95, v66, v67
	v_cndmask_b32_e32 v50, v89, v50, vcc
	v_cmp_gt_u32_e32 vcc, s7, v97
	v_subrev_u32_e32 v97, 24, v94
	v_mul_f32_e32 v54, 0x3e38aa3b, v54
	v_cndmask_b32_e32 v51, v89, v51, vcc
	v_cmp_gt_u32_e32 vcc, s7, v97
	v_subrev_u32_e32 v97, 23, v94
	v_max3_f32 v95, v95, v68, v69
	v_cndmask_b32_e32 v52, v89, v52, vcc
	v_cmp_gt_u32_e32 vcc, s7, v97
	v_subrev_u32_e32 v97, 22, v94
	v_mul_f32_e32 v55, 0x3e38aa3b, v55
	v_cndmask_b32_e32 v53, v89, v53, vcc
	v_cmp_gt_u32_e32 vcc, s7, v97
	v_subrev_u32_e32 v97, 21, v94
	v_max3_f32 v95, v95, v70, v71
	v_cndmask_b32_e32 v54, v89, v54, vcc
	v_cmp_gt_u32_e32 vcc, s7, v97
	v_add_u32_e32 v97, -16, v94
	v_mul_f32_e32 v56, 0x3e38aa3b, v56
	v_cndmask_b32_e32 v55, v89, v55, vcc
	v_cmp_gt_u32_e32 vcc, s7, v97
	v_add_u32_e32 v97, -15, v94
	v_max3_f32 v95, v95, v72, v73
	v_cndmask_b32_e32 v56, v89, v56, vcc
	v_mul_f32_e32 v57, 0x3e38aa3b, v57
	v_cmp_gt_u32_e32 vcc, s7, v97
	v_add_u32_e32 v97, -14, v94
	v_max3_f32 v95, v95, v74, v75
	v_cndmask_b32_e32 v57, v89, v57, vcc
	v_mul_f32_e32 v58, 0x3e38aa3b, v58
	v_cmp_gt_u32_e32 vcc, s7, v97
	v_add_u32_e32 v97, -13, v94
	v_max3_f32 v95, v95, v76, v77
	v_cndmask_b32_e32 v58, v89, v58, vcc
	v_mul_f32_e32 v59, 0x3e38aa3b, v59
	v_cmp_gt_u32_e32 vcc, s7, v97
	v_add_u32_e32 v97, -8, v94
	v_max3_f32 v95, v95, v78, v79
	v_cndmask_b32_e32 v59, v89, v59, vcc
	v_mul_f32_e32 v60, 0x3e38aa3b, v60
	v_cmp_gt_u32_e32 vcc, s7, v97
	v_add_u32_e32 v97, -7, v94
	v_max3_f32 v95, v95, v48, v49
	v_cndmask_b32_e32 v60, v89, v60, vcc
	v_mul_f32_e32 v61, 0x3e38aa3b, v61
	v_cmp_gt_u32_e32 vcc, s7, v97
	v_add_u32_e32 v97, -6, v94
	v_max3_f32 v95, v95, v50, v51
	v_cndmask_b32_e32 v61, v89, v61, vcc
	v_mul_f32_e32 v62, 0x3e38aa3b, v62
	v_cmp_gt_u32_e32 vcc, s7, v97
	v_add_u32_e32 v97, -5, v94
	v_max3_f32 v95, v95, v52, v53
	v_cndmask_b32_e32 v62, v89, v62, vcc
	v_mul_f32_e32 v63, 0x3e38aa3b, v63
; __device__ __forceinline__ int crow(int r, int hi) { return (r & 3) + 8 * (r >> 2) + 4 * hi; }
; __device__ __forceinline__ void dil_wave_item(const bf16* __restrict__ qkv, bf16* __restrict__ odil, float* __restrict__ lse,
;                               int pat, int g  , int head, char* wl  , const int W) {
;     ...
;   float mx = -1e30f;
; #pragma unroll
;   for (int kb = 0; kb < 5; ++kb)
; #pragma unroll
;     for (int r = 0; r < 16; ++r) {
;       const int rel = kb * 32 - 64 + crow(r, hi) - r32;
;       const int kc = i0 + r32 + rel;
;       const bool ok = (rel >= -64) && (rel <= 64) && (kc >= 0) && (kc < L);
;       const float s = ok ? sc[kb][r] * AC : -1e30f;
;       sc[kb][r] = s; mx = fmaxf(mx, s);
;     }
	v_cmp_gt_u32_e32 vcc, s7, v97
	v_max3_f32 v95, v95, v54, v55
	v_mul_f32_e32 v32, 0x3e38aa3b, v32
	v_cndmask_b32_e32 v63, v89, v63, vcc
	v_cmp_gt_u32_e32 vcc, s7, v94
	v_add_u32_e32 v96, v134, v96
	v_max3_f32 v95, v95, v56, v57
	v_cndmask_b32_e32 v32, v89, v32, vcc
	v_mul_f32_e32 v33, 0x3e38aa3b, v33
	v_cmp_gt_u32_e32 vcc, s7, v96
	v_add_u32_e32 v96, v134, v98
	v_max3_f32 v95, v95, v58, v59
	v_cndmask_b32_e32 v33, v89, v33, vcc
	v_mul_f32_e32 v34, 0x3e38aa3b, v34
	v_cmp_gt_u32_e32 vcc, s7, v96
	v_max3_f32 v95, v95, v60, v61
	v_max3_f32 v95, v95, v62, v63
	v_cndmask_b32_e32 v96, v89, v34, vcc
	v_add_u32_e32 v34, v134, v99
	v_mul_f32_e32 v35, 0x3e38aa3b, v35
	v_cmp_gt_u32_e32 vcc, s7, v34
	v_max3_f32 v95, v95, v32, v33
	v_mul_f32_e32 v36, 0x3e38aa3b, v36
	v_cndmask_b32_e32 v35, v89, v35, vcc
	v_max3_f32 v34, v95, v96, v35
	v_add_u32_e32 v95, v134, v100
	v_cmp_gt_u32_e32 vcc, s7, v95
	v_add_u32_e32 v95, v134, v101
	v_mul_f32_e32 v37, 0x3e38aa3b, v37
	v_cndmask_b32_e32 v36, v89, v36, vcc
	v_cmp_gt_u32_e32 vcc, s7, v95
	v_add_u32_e32 v95, v134, v102
	v_mul_f32_e32 v38, 0x3e38aa3b, v38
	v_cndmask_b32_e32 v37, v89, v37, vcc
	v_cmp_gt_u32_e32 vcc, s7, v95
	v_add_u32_e32 v95, v134, v103
	v_mul_f32_e32 v39, 0x3e38aa3b, v39
	v_cndmask_b32_e32 v38, v89, v38, vcc
	v_cmp_gt_u32_e32 vcc, s7, v95
	v_add_u32_e32 v95, v134, v104
	v_mfma_f32_32x32x16_bf16 v[16:31], v[114:117], v[126:129], v[16:31]
	v_cndmask_b32_e32 v39, v89, v39, vcc
	v_mul_f32_e32 v40, 0x3e38aa3b, v40
	v_cmp_gt_u32_e32 vcc, s7, v95
	v_add_u32_e32 v95, v134, v105
	v_mul_f32_e32 v41, 0x3e38aa3b, v41
	v_cndmask_b32_e32 v40, v89, v40, vcc
	v_cmp_gt_u32_e32 vcc, s7, v95
	v_add_u32_e32 v95, v134, v106
	v_mul_f32_e32 v42, 0x3e38aa3b, v42
	v_cndmask_b32_e32 v41, v89, v41, vcc
	v_cmp_gt_u32_e32 vcc, s7, v95
	v_add_u32_e32 v95, v134, v107
	v_mul_f32_e32 v43, 0x3e38aa3b, v43
	v_cndmask_b32_e32 v42, v89, v42, vcc
	v_cmp_gt_u32_e32 vcc, s7, v95
	v_add_u32_e32 v95, v134, v108
	v_mul_f32_e32 v44, 0x3e38aa3b, v44
	v_cndmask_b32_e32 v43, v89, v43, vcc
	v_cmp_gt_u32_e32 vcc, s7, v95
	v_add_u32_e32 v95, v134, v109
	v_mul_f32_e32 v45, 0x3e38aa3b, v45
	v_cndmask_b32_e32 v44, v89, v44, vcc
	v_cmp_gt_u32_e32 vcc, s7, v95
	v_add_u32_e32 v95, v134, v110
	v_mul_f32_e32 v46, 0x3e38aa3b, v46
	v_cndmask_b32_e32 v45, v89, v45, vcc
	v_cmp_gt_u32_e32 vcc, s7, v95
	v_add_u32_e32 v95, v134, v111
	v_mul_f32_e32 v47, 0x3e38aa3b, v47
	v_cndmask_b32_e32 v46, v89, v46, vcc
	v_cmp_gt_u32_e32 vcc, s7, v95
	v_add_u32_e32 v95, 32, v94
	v_mul_f32_e32 v16, 0x3e38aa3b, v16
	v_cndmask_b32_e32 v47, v89, v47, vcc
	v_cmp_gt_u32_e32 vcc, s7, v95
	v_add_u32_e32 v95, 33, v94
	v_mul_f32_e32 v17, 0x3e38aa3b, v17
	v_cndmask_b32_e32 v16, v89, v16, vcc
	v_cmp_gt_u32_e32 vcc, s7, v95
	v_add_u32_e32 v95, 34, v94
	v_mul_f32_e32 v18, 0x3e38aa3b, v18
	v_cndmask_b32_e32 v17, v89, v17, vcc
	v_cmp_gt_u32_e32 vcc, s7, v95
	v_add_u32_e32 v95, 35, v94
	v_mul_f32_e32 v19, 0x3e38aa3b, v19
	v_cndmask_b32_e32 v18, v89, v18, vcc
	v_cmp_gt_u32_e32 vcc, s7, v95
	v_add_u32_e32 v95, 40, v94
	v_mul_f32_e32 v20, 0x3e38aa3b, v20
	v_cndmask_b32_e32 v19, v89, v19, vcc
	v_cmp_gt_u32_e32 vcc, s7, v95
	v_add_u32_e32 v95, 41, v94
	v_mul_f32_e32 v21, 0x3e38aa3b, v21
	v_cndmask_b32_e32 v20, v89, v20, vcc
	v_cmp_gt_u32_e32 vcc, s7, v95
	v_add_u32_e32 v95, 42, v94
	v_mul_f32_e32 v22, 0x3e38aa3b, v22
	v_cndmask_b32_e32 v21, v89, v21, vcc
	v_cmp_gt_u32_e32 vcc, s7, v95
	v_add_u32_e32 v95, 43, v94
	v_mul_f32_e32 v23, 0x3e38aa3b, v23
	v_cndmask_b32_e32 v22, v89, v22, vcc
	v_cmp_gt_u32_e32 vcc, s7, v95
	v_add_u32_e32 v95, 48, v94
	v_max3_f32 v34, v34, v36, v37
	v_cndmask_b32_e32 v23, v89, v23, vcc
	v_mul_f32_e32 v24, 0x3e38aa3b, v24
	v_cmp_gt_u32_e32 vcc, s7, v95
	v_add_u32_e32 v95, 49, v94
	v_max3_f32 v34, v34, v38, v39
	v_cndmask_b32_e32 v24, v89, v24, vcc
	v_mul_f32_e32 v25, 0x3e38aa3b, v25
	v_cmp_gt_u32_e32 vcc, s7, v95
	v_add_u32_e32 v95, 50, v94
	v_max3_f32 v34, v34, v40, v41
	v_cndmask_b32_e32 v25, v89, v25, vcc
	v_mul_f32_e32 v26, 0x3e38aa3b, v26
	v_cmp_gt_u32_e32 vcc, s7, v95
	v_add_u32_e32 v95, 51, v94
	v_max3_f32 v34, v34, v42, v43
	v_cndmask_b32_e32 v26, v89, v26, vcc
	v_mul_f32_e32 v27, 0x3e38aa3b, v27
	v_cmp_gt_u32_e32 vcc, s7, v95
	v_add_u32_e32 v95, 56, v94
	v_max3_f32 v34, v34, v44, v45
	v_cndmask_b32_e32 v27, v89, v27, vcc
	v_mul_f32_e32 v28, 0x3e38aa3b, v28
	v_cmp_gt_u32_e32 vcc, s7, v95
	v_add_u32_e32 v95, 57, v94
	v_max3_f32 v34, v34, v46, v47
	v_cndmask_b32_e32 v28, v89, v28, vcc
	v_mul_f32_e32 v29, 0x3e38aa3b, v29
	v_cmp_gt_u32_e32 vcc, s7, v95
	v_add_u32_e32 v95, 58, v94
	v_max3_f32 v34, v34, v16, v17
	v_cndmask_b32_e32 v29, v89, v29, vcc
	v_mul_f32_e32 v30, 0x3e38aa3b, v30
	v_cmp_gt_u32_e32 vcc, s7, v95
	v_add_u32_e32 v95, 59, v94
	v_max3_f32 v34, v34, v18, v19
	v_cndmask_b32_e32 v30, v89, v30, vcc
	v_mul_f32_e32 v31, 0x3e38aa3b, v31
	v_cmp_gt_u32_e32 vcc, s7, v95
	v_add_u32_e32 v95, 64, v94
	v_add_u32_e32 v97, 0x80, v93
	v_max3_f32 v34, v34, v20, v21
	v_cndmask_b32_e32 v31, v89, v31, vcc
	v_cmp_gt_u32_e32 vcc, s64, v97
	v_cmp_gt_u32_e64 s[4:5], s7, v95
	v_max3_f32 v34, v34, v22, v23
	v_mul_f32_e32 v0, 0x3e38aa3b, v0
	s_and_b64 vcc, vcc, s[4:5]
	v_max3_f32 v34, v34, v24, v25
	v_cndmask_b32_e32 v98, v89, v0, vcc
	v_add_u32_e32 v0, 0x41, v94
	v_max3_f32 v34, v34, v26, v27
	v_cmp_lt_u32_e32 vcc, s68, v93
	v_cmp_gt_u32_e64 s[4:5], s7, v0
	v_max3_f32 v34, v34, v28, v29
	v_mul_f32_e32 v0, 0x3e38aa3b, v1
	s_and_b64 vcc, vcc, s[4:5]
	v_max3_f32 v34, v34, v30, v31
	v_cndmask_b32_e32 v99, v89, v0, vcc
	v_max3_f32 v0, v34, v98, v99
	v_add_u32_e32 v1, 0x42, v94
	v_add_u32_e32 v34, 0x82, v93
	v_cmp_gt_u32_e32 vcc, s64, v34
	v_cmp_gt_u32_e64 s[4:5], s7, v1
; __device__ __forceinline__ float shfl_idx(float v, int srclane) { return __int_as_float(__builtin_amdgcn_ds_bpermute(srclane << 2, __float_as_int(v))); }
; __device__ __forceinline__ int crow(int r, int hi) { return (r & 3) + 8 * (r >> 2) + 4 * hi; }
; __device__ __forceinline__ void dil_wave_item(const bf16* __restrict__ qkv, bf16* __restrict__ odil, float* __restrict__ lse,
;                               int pat, int g  , int head, char* wl  , const int W) {
;     ...
;   float mx = -1e30f;
; #pragma unroll
;   for (int kb = 0; kb < 5; ++kb)
; #pragma unroll
;     for (int r = 0; r < 16; ++r) {
;       const int rel = kb * 32 - 64 + crow(r, hi) - r32;
;       const int kc = i0 + r32 + rel;
;       const bool ok = (rel >= -64) && (rel <= 64) && (kc >= 0) && (kc < L);
;       const float s = ok ? sc[kb][r] * AC : -1e30f;
;       sc[kb][r] = s; mx = fmaxf(mx, s);
;     }
;   mx = fmaxf(mx, shfl_idx(mx, lane ^ 32));
;   float ls = 0.f;
; #pragma unroll
;   for (int kb = 0; kb < 5; ++kb)
; #pragma unroll
;     for (int r = 0; r < 16; ++r) { const float e = __builtin_amdgcn_exp2f(sc[kb][r] - mx); sc[kb][r] = e; ls += e; }
;   ls += shfl_idx(ls, lane ^ 32);
	v_mul_f32_e32 v1, 0x3e38aa3b, v2
	s_and_b64 vcc, vcc, s[4:5]
	v_cndmask_b32_e32 v100, v89, v1, vcc
	v_add_u32_e32 v1, 0x43, v94
	v_add_u32_e32 v2, 0x83, v93
	v_cmp_gt_u32_e32 vcc, s64, v2
	v_cmp_gt_u32_e64 s[4:5], s7, v1
	v_mul_f32_e32 v1, 0x3e38aa3b, v3
	s_and_b64 vcc, vcc, s[4:5]
	v_cndmask_b32_e32 v101, v89, v1, vcc
	v_add_u32_e32 v1, 0x48, v94
	v_add_u32_e32 v2, 0x88, v93
	v_cmp_gt_u32_e32 vcc, s64, v2
	v_cmp_gt_u32_e64 s[4:5], s7, v1
	v_mul_f32_e32 v1, 0x3e38aa3b, v4
	s_and_b64 vcc, vcc, s[4:5]
	v_cndmask_b32_e32 v102, v89, v1, vcc
	v_add_u32_e32 v1, 0x49, v94
	v_add_u32_e32 v2, 0x89, v93
	v_cmp_gt_u32_e32 vcc, s64, v2
	v_cmp_gt_u32_e64 s[4:5], s7, v1
	v_mul_f32_e32 v1, 0x3e38aa3b, v5
	s_and_b64 vcc, vcc, s[4:5]
	v_cndmask_b32_e32 v103, v89, v1, vcc
	v_add_u32_e32 v1, 0x4a, v94
	v_add_u32_e32 v2, 0x8a, v93
	v_cmp_gt_u32_e32 vcc, s64, v2
	v_cmp_gt_u32_e64 s[4:5], s7, v1
	v_mul_f32_e32 v1, 0x3e38aa3b, v6
	s_and_b64 vcc, vcc, s[4:5]
	v_cndmask_b32_e32 v104, v89, v1, vcc
	v_add_u32_e32 v1, 0x4b, v94
	v_add_u32_e32 v2, 0x8b, v93
	v_cmp_gt_u32_e32 vcc, s64, v2
	v_cmp_gt_u32_e64 s[4:5], s7, v1
	v_mul_f32_e32 v1, 0x3e38aa3b, v7
	s_and_b64 vcc, vcc, s[4:5]
	v_cndmask_b32_e32 v105, v89, v1, vcc
	v_add_u32_e32 v1, 0x50, v94
	v_add_u32_e32 v2, 0x90, v93
	v_cmp_gt_u32_e32 vcc, s64, v2
	v_cmp_gt_u32_e64 s[4:5], s7, v1
	v_mul_f32_e32 v1, 0x3e38aa3b, v8
	s_and_b64 vcc, vcc, s[4:5]
	v_cndmask_b32_e32 v106, v89, v1, vcc
	v_add_u32_e32 v1, 0x51, v94
	v_add_u32_e32 v2, 0x91, v93
	v_cmp_gt_u32_e32 vcc, s64, v2
	v_cmp_gt_u32_e64 s[4:5], s7, v1
	v_mul_f32_e32 v1, 0x3e38aa3b, v9
	s_and_b64 vcc, vcc, s[4:5]
	v_cndmask_b32_e32 v107, v89, v1, vcc
	v_add_u32_e32 v1, 0x52, v94
	v_add_u32_e32 v2, 0x92, v93
	v_cmp_gt_u32_e32 vcc, s64, v2
	v_cmp_gt_u32_e64 s[4:5], s7, v1
	v_mul_f32_e32 v1, 0x3e38aa3b, v10
	s_and_b64 vcc, vcc, s[4:5]
	v_cndmask_b32_e32 v108, v89, v1, vcc
	v_add_u32_e32 v1, 0x53, v94
	v_add_u32_e32 v2, 0x93, v93
	v_cmp_gt_u32_e32 vcc, s64, v2
	v_cmp_gt_u32_e64 s[4:5], s7, v1
	v_mul_f32_e32 v1, 0x3e38aa3b, v11
	s_and_b64 vcc, vcc, s[4:5]
	v_cndmask_b32_e32 v109, v89, v1, vcc
	v_add_u32_e32 v1, 0x58, v94
	v_add_u32_e32 v2, 0x98, v93
	v_cmp_gt_u32_e32 vcc, s64, v2
	v_cmp_gt_u32_e64 s[4:5], s7, v1
	v_mul_f32_e32 v1, 0x3e38aa3b, v12
	s_and_b64 vcc, vcc, s[4:5]
	v_cndmask_b32_e32 v110, v89, v1, vcc
	v_add_u32_e32 v1, 0x59, v94
	v_add_u32_e32 v2, 0x99, v93
	v_cmp_gt_u32_e32 vcc, s64, v2
	v_cmp_gt_u32_e64 s[4:5], s7, v1
	v_mul_f32_e32 v1, 0x3e38aa3b, v13
	s_and_b64 vcc, vcc, s[4:5]
	v_cndmask_b32_e32 v111, v89, v1, vcc
	v_add_u32_e32 v1, 0x5a, v94
	v_add_u32_e32 v2, 0x9a, v93
	v_max3_f32 v0, v0, v100, v101
	v_cmp_gt_u32_e32 vcc, s64, v2
	v_cmp_gt_u32_e64 s[4:5], s7, v1
	v_max3_f32 v0, v0, v102, v103
	v_mul_f32_e32 v1, 0x3e38aa3b, v14
	s_and_b64 vcc, vcc, s[4:5]
	v_max3_f32 v0, v0, v104, v105
	v_cndmask_b32_e32 v112, v89, v1, vcc
	v_add_u32_e32 v1, 0x5b, v94
	v_add_u32_e32 v2, 0x9b, v93
	v_max3_f32 v0, v0, v106, v107
	v_cmp_gt_u32_e32 vcc, s64, v2
	v_cmp_gt_u32_e64 s[4:5], s7, v1
	v_max3_f32 v0, v0, v108, v109
	v_mul_f32_e32 v1, 0x3e38aa3b, v15
	s_and_b64 vcc, vcc, s[4:5]
	v_max3_f32 v0, v0, v110, v111
	v_cndmask_b32_e32 v113, v89, v1, vcc
	v_lshlrev_b32_e32 v1, 2, v87
	v_max3_f32 v0, v0, v112, v113
	v_xor_b32_e32 v114, 0x80, v1
	ds_bpermute_b32 v1, v114, v0
	s_waitcnt lgkmcnt(0)
	v_max_f32_e32 v1, v1, v1
	v_max_f32_e32 v34, v0, v1
	v_sub_f32_e32 v0, v64, v34
	v_exp_f32_e32 v115, v0
	v_sub_f32_e32 v0, v65, v34
	v_exp_f32_e32 v116, v0
	v_sub_f32_e32 v0, v66, v34
	v_exp_f32_e32 v117, v0
	v_sub_f32_e32 v0, v67, v34
	v_exp_f32_e32 v118, v0
	v_sub_f32_e32 v1, v68, v34
	v_add_f32_e32 v0, 0, v115
	v_exp_f32_e32 v119, v1
	v_sub_f32_e32 v1, v69, v34
	v_add_f32_e32 v0, v116, v0
	v_exp_f32_e32 v120, v1
	v_sub_f32_e32 v1, v70, v34
	v_add_f32_e32 v0, v117, v0
	v_exp_f32_e32 v121, v1
	v_sub_f32_e32 v1, v71, v34
	v_add_f32_e32 v0, v118, v0
	v_exp_f32_e32 v122, v1
	v_sub_f32_e32 v1, v72, v34
	v_add_f32_e32 v0, v119, v0
	v_exp_f32_e32 v123, v1
	v_sub_f32_e32 v1, v73, v34
	v_add_f32_e32 v0, v120, v0
	v_exp_f32_e32 v124, v1
	v_sub_f32_e32 v1, v74, v34
	v_add_f32_e32 v0, v121, v0
	v_exp_f32_e32 v125, v1
	v_sub_f32_e32 v1, v75, v34
	v_add_f32_e32 v0, v122, v0
	v_exp_f32_e32 v126, v1
	v_sub_f32_e32 v1, v76, v34
	v_add_f32_e32 v0, v123, v0
	v_exp_f32_e32 v127, v1
	v_sub_f32_e32 v1, v77, v34
	v_add_f32_e32 v0, v124, v0
	v_exp_f32_e32 v128, v1
	v_sub_f32_e32 v1, v78, v34
	v_add_f32_e32 v0, v125, v0
	v_exp_f32_e32 v129, v1
	v_sub_f32_e32 v1, v79, v34
	v_add_f32_e32 v0, v126, v0
	v_exp_f32_e32 v130, v1
	v_sub_f32_e32 v1, v48, v34
	v_add_f32_e32 v0, v127, v0
	v_exp_f32_e32 v131, v1
	v_sub_f32_e32 v1, v49, v34
	v_add_f32_e32 v0, v128, v0
	v_exp_f32_e32 v132, v1
	v_sub_f32_e32 v1, v50, v34
	v_add_f32_e32 v0, v129, v0
	v_exp_f32_e32 v133, v1
	v_sub_f32_e32 v1, v51, v34
	v_add_f32_e32 v0, v130, v0
	v_exp_f32_e32 v134, v1
	v_sub_f32_e32 v1, v52, v34
	v_add_f32_e32 v0, v131, v0
	v_exp_f32_e32 v135, v1
	v_sub_f32_e32 v1, v53, v34
	v_add_f32_e32 v0, v132, v0
	v_exp_f32_e32 v136, v1
	v_sub_f32_e32 v1, v54, v34
	v_add_f32_e32 v0, v133, v0
	v_exp_f32_e32 v137, v1
	v_sub_f32_e32 v1, v55, v34
	v_add_f32_e32 v0, v134, v0
	v_exp_f32_e32 v138, v1
	v_sub_f32_e32 v1, v56, v34
	v_add_f32_e32 v0, v135, v0
	v_exp_f32_e32 v139, v1
	v_sub_f32_e32 v1, v57, v34
	v_add_f32_e32 v0, v136, v0
	v_exp_f32_e32 v140, v1
	v_sub_f32_e32 v1, v58, v34
	v_add_f32_e32 v0, v137, v0
	v_exp_f32_e32 v141, v1
	v_sub_f32_e32 v1, v59, v34
	v_add_f32_e32 v0, v138, v0
	v_exp_f32_e32 v142, v1
	v_sub_f32_e32 v1, v60, v34
	v_add_f32_e32 v0, v139, v0
	v_exp_f32_e32 v143, v1
	v_sub_f32_e32 v1, v61, v34
	v_add_f32_e32 v0, v140, v0
; __device__ __forceinline__ float shfl_idx(float v, int srclane) { return __int_as_float(__builtin_amdgcn_ds_bpermute(srclane << 2, __float_as_int(v))); }
; __device__ __forceinline__ int v_st2(int k, int c) { const int kk = (k & ~0xC) | ((k & 4) << 1) | ((k & 8) >> 1); return ((kk >> 3) * 2 + (c >> 5)) * 512 + ((kk & 7) * 32 + (c & 31)) * 2; }
; __device__ __forceinline__ int v_rd_base(int lane) { return ((lane & 3) << 3) | (((lane >> 2) & 3) << 6) | (((lane >> 4) & 1) << 5) | (((lane >> 5) & 1) << 8); }
; __device__ __forceinline__ void dil_wave_item(const bf16* __restrict__ qkv, bf16* __restrict__ odil, float* __restrict__ lse,
;                               int pat, int g  , int head, char* wl  , const int W) {
;     ...
;   float ls = 0.f;
; #pragma unroll
;   for (int kb = 0; kb < 5; ++kb)
; #pragma unroll
;     for (int r = 0; r < 16; ++r) { const float e = __builtin_amdgcn_exp2f(sc[kb][r] - mx); sc[kb][r] = e; ls += e; }
;   ls += shfl_idx(ls, lane ^ 32);
;   f32x16 o0 = {}, o1 = {};
;   const int vb = (int)(uintptr_t)wl + v_rd_base(lane);
; #pragma unroll
;   for (int kb = 0; kb < 5; ++kb) {
;     bf16x8 vr[4];
; #pragma unroll
;     for (int i = 0; i < 4; ++i) {
;       const int key = i * 8 + (lane >> 3);
;       int kc = i0 - 64 + kb * 32 + key; kc = min(max(kc, 0), L - 1);
;       vr[i] = *reinterpret_cast<const bf16x8*>(qkv + (size_t)(tbase + kc * dil) * LDQ + 2560 + head * 64 + (lane & 7) * 8);
;     }
; #pragma unroll
;     for (int i = 0; i < 4; ++i) *reinterpret_cast<bf16x8*>(wl + v_st2(i * 8 + (lane >> 3), (lane & 7) * 8)) = vr[i];
	v_exp_f32_e32 v144, v1
	v_sub_f32_e32 v1, v62, v34
	v_add_f32_e32 v0, v141, v0
	v_exp_f32_e32 v145, v1
	v_sub_f32_e32 v1, v63, v34
	v_add_f32_e32 v0, v142, v0
	v_exp_f32_e32 v146, v1
	v_sub_f32_e32 v1, v32, v34
	v_add_f32_e32 v0, v143, v0
	v_exp_f32_e32 v56, v1
	v_sub_f32_e32 v1, v33, v34
	v_add_f32_e32 v0, v144, v0
	v_exp_f32_e32 v57, v1
	v_sub_f32_e32 v1, v96, v34
	v_add_f32_e32 v0, v145, v0
	v_exp_f32_e32 v60, v1
	v_sub_f32_e32 v1, v35, v34
	v_add_f32_e32 v0, v146, v0
	v_exp_f32_e32 v65, v1
	v_sub_f32_e32 v1, v36, v34
	v_add_f32_e32 v0, v56, v0
	v_exp_f32_e32 v69, v1
	v_sub_f32_e32 v1, v37, v34
	v_add_f32_e32 v0, v57, v0
	v_exp_f32_e32 v71, v1
	v_sub_f32_e32 v1, v38, v34
	v_add_f32_e32 v0, v60, v0
	v_exp_f32_e32 v75, v1
	v_sub_f32_e32 v1, v39, v34
	v_add_f32_e32 v0, v65, v0
	v_exp_f32_e32 v78, v1
	v_sub_f32_e32 v1, v40, v34
	v_add_f32_e32 v0, v69, v0
	v_exp_f32_e32 v72, v1
	v_sub_f32_e32 v1, v41, v34
	v_add_f32_e32 v0, v71, v0
	v_exp_f32_e32 v76, v1
	v_sub_f32_e32 v1, v42, v34
	v_add_f32_e32 v0, v75, v0
	v_exp_f32_e32 v79, v1
	v_sub_f32_e32 v1, v43, v34
	v_add_f32_e32 v0, v78, v0
	v_exp_f32_e32 v93, v1
	v_sub_f32_e32 v1, v44, v34
	v_add_f32_e32 v0, v72, v0
	v_exp_f32_e32 v94, v1
	v_sub_f32_e32 v1, v45, v34
	v_add_f32_e32 v0, v76, v0
	v_exp_f32_e32 v95, v1
	v_sub_f32_e32 v1, v46, v34
	v_add_f32_e32 v0, v79, v0
	v_exp_f32_e32 v96, v1
	v_sub_f32_e32 v1, v47, v34
	v_add_f32_e32 v0, v93, v0
	v_exp_f32_e32 v97, v1
	v_sub_f32_e32 v1, v16, v34
	v_add_f32_e32 v0, v94, v0
	v_exp_f32_e32 v35, v1
	v_sub_f32_e32 v1, v17, v34
	v_add_f32_e32 v0, v95, v0
	v_exp_f32_e32 v36, v1
	v_sub_f32_e32 v1, v18, v34
	v_add_f32_e32 v0, v96, v0
	v_exp_f32_e32 v37, v1
	v_sub_f32_e32 v1, v19, v34
	v_add_f32_e32 v0, v97, v0
	v_exp_f32_e32 v38, v1
	v_sub_f32_e32 v1, v20, v34
	v_add_f32_e32 v0, v35, v0
	v_exp_f32_e32 v42, v1
	v_sub_f32_e32 v1, v21, v34
	v_add_f32_e32 v0, v36, v0
	v_exp_f32_e32 v43, v1
	v_sub_f32_e32 v1, v22, v34
	v_add_f32_e32 v0, v37, v0
	v_exp_f32_e32 v45, v1
	v_sub_f32_e32 v1, v23, v34
	v_add_f32_e32 v0, v38, v0
	v_exp_f32_e32 v47, v1
	v_sub_f32_e32 v1, v24, v34
	v_add_f32_e32 v0, v42, v0
	v_exp_f32_e32 v44, v1
	v_sub_f32_e32 v1, v25, v34
	v_add_f32_e32 v0, v43, v0
	v_exp_f32_e32 v46, v1
	v_sub_f32_e32 v1, v26, v34
	v_add_f32_e32 v0, v45, v0
	v_exp_f32_e32 v48, v1
	v_sub_f32_e32 v1, v27, v34
	v_add_f32_e32 v0, v47, v0
	v_exp_f32_e32 v49, v1
	v_add_f32_e32 v0, v44, v0
	v_add_f32_e32 v0, v46, v0
	v_add_f32_e32 v0, v48, v0
	v_bfe_u32 v17, v92, 3, 3
	v_add_f32_e32 v16, v49, v0
	v_sub_f32_e32 v0, v28, v34
	v_or_b32_e32 v10, s78, v17
	v_exp_f32_e32 v50, v0
	v_sub_f32_e32 v0, v29, v34
	v_subrev_u32_e32 v39, 64, v10
	v_lshlrev_b32_e32 v18, 3, v92
	v_exp_f32_e32 v51, v0
	v_and_b32_e32 v2, 56, v18
	v_max_i32_e32 v0, 0, v39
	v_min_u32_e32 v0, s6, v0
	v_lshlrev_b32_e32 v32, 1, v2
	v_subrev_u32_e32 v2, 56, v10
	v_lshlrev_b32_e32 v0, s71, v0
	v_max_i32_e32 v2, 0, v2
	v_add_u32_e32 v0, s79, v0
	v_min_u32_e32 v2, s6, v2
	v_subrev_u32_e32 v8, 48, v10
	v_mad_i64_i32 v[0:1], s[4:5], v0, s62, v[84:85]
	v_lshlrev_b32_e32 v2, s71, v2
	v_max_i32_e32 v8, 0, v8
	v_lshl_add_u64 v[0:1], v[0:1], 0, s[74:75]
	v_mov_b32_e32 v33, v83
	v_add_u32_e32 v2, s79, v2
	v_min_u32_e32 v8, s6, v8
	v_subrev_u32_e32 v10, 40, v10
	v_lshl_add_u64 v[0:1], v[0:1], 0, v[32:33]
	v_mad_i64_i32 v[2:3], s[4:5], v2, s62, v[84:85]
	v_lshlrev_b32_e32 v8, s71, v8
	v_max_i32_e32 v10, 0, v10
	v_add_co_u32_e32 v0, vcc, s63, v0
	v_lshl_add_u64 v[2:3], v[2:3], 0, s[74:75]
	v_add_u32_e32 v8, s79, v8
	v_min_u32_e32 v10, s6, v10
	v_addc_co_u32_e32 v1, vcc, 0, v1, vcc
	v_lshl_add_u64 v[2:3], v[2:3], 0, v[32:33]
	v_mad_i64_i32 v[8:9], s[4:5], v8, s62, v[84:85]
	v_lshlrev_b32_e32 v10, s71, v10
	v_add_co_u32_e32 v4, vcc, s63, v2
	v_lshl_add_u64 v[8:9], v[8:9], 0, s[74:75]
	v_add_u32_e32 v10, s79, v10
	v_addc_co_u32_e32 v5, vcc, 0, v3, vcc
	v_lshl_add_u64 v[8:9], v[8:9], 0, v[32:33]
	v_mad_i64_i32 v[10:11], s[4:5], v10, s62, v[84:85]
	v_add_co_u32_e32 v8, vcc, s63, v8
	v_lshl_add_u64 v[10:11], v[10:11], 0, s[74:75]
	s_nop 0
	v_addc_co_u32_e32 v9, vcc, 0, v9, vcc
	v_lshl_add_u64 v[10:11], v[10:11], 0, v[32:33]
	v_add_co_u32_e32 v12, vcc, s63, v10
	s_nop 0
	v_addc_co_u32_e32 v13, vcc, 0, v11, vcc
	s_nop 0
	v_sub_f32_e32 v19, v30, v34
	v_exp_f32_e32 v147, v19
	v_sub_f32_e32 v19, v31, v34
	v_exp_f32_e32 v148, v19
	v_sub_f32_e32 v19, v98, v34
	v_add_f32_e32 v16, v50, v16
	v_exp_f32_e32 v52, v19
	v_sub_f32_e32 v19, v99, v34
	v_add_f32_e32 v16, v51, v16
	v_exp_f32_e32 v53, v19
	v_sub_f32_e32 v19, v100, v34
	v_add_f32_e32 v16, v147, v16
	v_exp_f32_e32 v54, v19
	v_sub_f32_e32 v19, v101, v34
	v_add_f32_e32 v16, v148, v16
	v_exp_f32_e32 v55, v19
	v_sub_f32_e32 v19, v102, v34
	v_add_f32_e32 v16, v52, v16
	v_exp_f32_e32 v58, v19
	v_sub_f32_e32 v19, v103, v34
	v_add_f32_e32 v16, v53, v16
	v_exp_f32_e32 v61, v19
	v_sub_f32_e32 v19, v104, v34
	v_add_f32_e32 v16, v54, v16
	v_exp_f32_e32 v63, v19
	v_sub_f32_e32 v19, v105, v34
	v_add_f32_e32 v16, v55, v16
	v_exp_f32_e32 v66, v19
	v_sub_f32_e32 v19, v106, v34
	v_add_f32_e32 v16, v58, v16
	v_exp_f32_e32 v59, v19
	v_sub_f32_e32 v19, v107, v34
	v_add_f32_e32 v16, v61, v16
	v_exp_f32_e32 v62, v19
	v_sub_f32_e32 v19, v108, v34
	v_add_f32_e32 v16, v63, v16
	v_exp_f32_e32 v64, v19
	v_sub_f32_e32 v19, v109, v34
	v_add_f32_e32 v16, v66, v16
	v_exp_f32_e32 v67, v19
	v_sub_f32_e32 v19, v110, v34
	v_add_f32_e32 v16, v59, v16
	v_exp_f32_e32 v70, v19
	v_sub_f32_e32 v19, v111, v34
	v_add_f32_e32 v16, v62, v16
	v_exp_f32_e32 v73, v19
	v_sub_f32_e32 v19, v112, v34
	v_add_f32_e32 v16, v64, v16
	v_exp_f32_e32 v74, v19
	v_sub_f32_e32 v19, v113, v34
	v_add_f32_e32 v16, v67, v16
	v_exp_f32_e32 v77, v19
	v_add_f32_e32 v16, v70, v16
	v_add_f32_e32 v16, v73, v16
	v_add_f32_e32 v16, v74, v16
	v_lshlrev_b32_e32 v19, 4, v92
	v_add_f32_e32 v40, v77, v16
	v_lshlrev_b32_e32 v16, 3, v87
	v_and_b32_e32 v20, 0xc0, v19
	v_lshlrev_b32_e32 v21, 1, v92
	v_and_or_b32 v20, v16, 24, v20
	v_and_b32_e32 v21, 32, v21
	v_and_b32_e32 v16, 0x100, v16
	v_or3_b32 v16, v20, v21, v16
	v_add_u32_e32 v68, s55, v16
	v_bfe_u32 v16, v18, 5, 1
	v_and_b32_e32 v18, 48, v19
	v_lshrrev_b32_e32 v19, 4, v92
	v_and_or_b32 v16, v19, 2, v16
	v_lshlrev_b32_e32 v17, 6, v17
	v_and_or_b32 v19, v17, s69, v18
	v_lshl_add_u32 v16, v16, 9, s55
	v_add_u32_e32 v149, v16, v19
	ds_bpermute_b32 v41, v114, v40
	s_waitcnt vmcnt(16)
; #define SBAR() __builtin_amdgcn_sched_barrier(0)
; __device__ __forceinline__ int v_st2(int k, int c) { const int kk = (k & ~0xC) | ((k & 4) << 1) | ((k & 8) >> 1); return ((kk >> 3) * 2 + (c >> 5)) * 512 + ((kk & 7) * 32 + (c & 31)) * 2; }
; __device__ __forceinline__ void dil_wave_item(const bf16* __restrict__ qkv, bf16* __restrict__ odil, float* __restrict__ lse,
;                               int pat, int g  , int head, char* wl  , const int W) {
;     ...
; #pragma unroll
;   for (int kb = 0; kb < 5; ++kb) {
;     bf16x8 vr[4];
; #pragma unroll
;     for (int i = 0; i < 4; ++i) {
;       const int key = i * 8 + (lane >> 3);
;       int kc = i0 - 64 + kb * 32 + key; kc = min(max(kc, 0), L - 1);
;       vr[i] = *reinterpret_cast<const bf16x8*>(qkv + (size_t)(tbase + kc * dil) * LDQ + 2560 + head * 64 + (lane & 7) * 8);
;     }
; #pragma unroll
;     for (int i = 0; i < 4; ++i) *reinterpret_cast<bf16x8*>(wl + v_st2(i * 8 + (lane >> 3), (lane & 7) * 8)) = vr[i];
;     bf16x8 pa0, pa1;
;     PK4(sc[kb], 0, pa0); PK4(sc[kb], 8, pa1);
;     asm volatile("s_waitcnt lgkmcnt(0)" ::: "memory");
;     const s16x4 a0 = tr_read<v_rd_off2(0, 0, 0)>(vb), b0 = tr_read<v_rd_off2(0, 0, 1)>(vb), a1 = tr_read<v_rd_off2(0, 1, 0)>(vb), b1 = tr_read<v_rd_off2(0, 1, 1)>(vb);
;     const s16x4 c0 = tr_read<v_rd_off2(1, 0, 0)>(vb), d0_ = tr_read<v_rd_off2(1, 0, 1)>(vb), c1 = tr_read<v_rd_off2(1, 1, 0)>(vb), d1 = tr_read<v_rd_off2(1, 1, 1)>(vb);
;     asm volatile("s_waitcnt lgkmcnt(0)" ::: "memory"); SBAR();
;     o0 = __builtin_amdgcn_mfma_f32_32x32x16_bf16(pa0, PKV(a0, b0), o0, 0, 0, 0);
;     o0 = __builtin_amdgcn_mfma_f32_32x32x16_bf16(pa1, PKV(a1, b1), o0, 0, 0, 0);
;     o1 = __builtin_amdgcn_mfma_f32_32x32x16_bf16(pa0, PKV(c0, d0_), o1, 0, 0, 0);
;     o1 = __builtin_amdgcn_mfma_f32_32x32x16_bf16(pa1, PKV(c1, d1), o1, 0, 0, 0);
;     SBAR();
;   }
;   if (hi == 0) lse[((size_t)pat * T + tbase + (i0 + r32) * dil) * 8 + head] = mx + __log2f(ls);
;   const float rl = __builtin_amdgcn_rcpf(ls);
	ds_write_b128 v149, v[152:155]
	v_or3_b32 v0, v17, v18, s61
	v_add_u32_e32 v150, v16, v0
	ds_write_b128 v150, v[156:159]
	ds_write_b128 v149, v[160:163] offset:2048
	ds_write_b128 v150, v[164:167] offset:2048
	v_cvt_pk_bf16_f32 v16, v115, v116
	v_cvt_pk_bf16_f32 v17, v117, v118
	v_cvt_pk_bf16_f32 v18, v119, v120
	v_cvt_pk_bf16_f32 v19, v121, v122
	v_cvt_pk_bf16_f32 v98, v123, v124
	v_cvt_pk_bf16_f32 v99, v125, v126
	v_cvt_pk_bf16_f32 v100, v127, v128
	v_cvt_pk_bf16_f32 v101, v129, v130
	s_waitcnt lgkmcnt(0)
	ds_read_b64_tr_b16 v[0:1], v68 offset:0
	ds_read_b64_tr_b16 v[2:3], v68 offset:0x400
	ds_read_b64_tr_b16 v[20:21], v68 offset:0x800
	ds_read_b64_tr_b16 v[22:23], v68 offset:0xc00
	ds_read_b64_tr_b16 v[24:25], v68 offset:0x200
	ds_read_b64_tr_b16 v[26:27], v68 offset:0x600
	ds_read_b64_tr_b16 v[102:103], v68 offset:0xa00
	ds_read_b64_tr_b16 v[104:105], v68 offset:0xe00
	s_waitcnt lgkmcnt(0)
	s_nop 0
	v_permlane32_swap_b32_e32 v16, v18
	v_permlane32_swap_b32_e32 v17, v19
	v_permlane32_swap_b32_e32 v98, v100
	v_permlane32_swap_b32_e32 v99, v101
	v_mfma_f32_32x32x16_bf16 v[0:15], v[0:3], v[16:19], 0
	s_nop 0
	v_mfma_f32_32x32x16_bf16 v[0:15], v[20:23], v[98:101], v[0:15]
	v_mfma_f32_32x32x16_bf16 v[16:31], v[24:27], v[16:19], 0
	v_mfma_f32_32x32x16_bf16 v[16:31], v[102:105], v[98:101], v[16:31]
	s_waitcnt vmcnt(12)
	ds_write_b128 v149, v[168:171]
	ds_write_b128 v150, v[172:175]
	ds_write_b128 v149, v[176:179] offset:2048
	ds_write_b128 v150, v[180:183] offset:2048
	v_cvt_pk_bf16_f32 v98, v131, v132
	v_cvt_pk_bf16_f32 v99, v133, v134
	v_cvt_pk_bf16_f32 v100, v135, v136
	v_cvt_pk_bf16_f32 v101, v137, v138
	v_cvt_pk_bf16_f32 v102, v139, v140
	v_cvt_pk_bf16_f32 v103, v141, v142
	v_cvt_pk_bf16_f32 v104, v143, v144
	v_cvt_pk_bf16_f32 v105, v145, v146
	s_waitcnt lgkmcnt(0)
	ds_read_b64_tr_b16 v[106:107], v68 offset:0
	ds_read_b64_tr_b16 v[108:109], v68 offset:0x400
	ds_read_b64_tr_b16 v[110:111], v68 offset:0x800
	ds_read_b64_tr_b16 v[112:113], v68 offset:0xc00
	ds_read_b64_tr_b16 v[114:115], v68 offset:0x200
	ds_read_b64_tr_b16 v[116:117], v68 offset:0x600
	ds_read_b64_tr_b16 v[118:119], v68 offset:0xa00
	ds_read_b64_tr_b16 v[120:121], v68 offset:0xe00
	s_waitcnt lgkmcnt(0)
	s_nop 0
	v_permlane32_swap_b32_e32 v98, v100
	v_permlane32_swap_b32_e32 v99, v101
	v_permlane32_swap_b32_e32 v102, v104
	v_permlane32_swap_b32_e32 v103, v105
	v_mfma_f32_32x32x16_bf16 v[0:15], v[106:109], v[98:101], v[0:15]
	v_mfma_f32_32x32x16_bf16 v[16:31], v[114:117], v[98:101], v[16:31]
	v_mfma_f32_32x32x16_bf16 v[0:15], v[110:113], v[102:105], v[0:15]
	v_mfma_f32_32x32x16_bf16 v[16:31], v[118:121], v[102:105], v[16:31]
	s_waitcnt vmcnt(8)
	ds_write_b128 v149, v[184:187]
	ds_write_b128 v150, v[188:191]
	ds_write_b128 v149, v[192:195] offset:2048
	ds_write_b128 v150, v[196:199] offset:2048
	v_cvt_pk_bf16_f32 v98, v56, v57
	v_cvt_pk_bf16_f32 v99, v60, v65
	v_cvt_pk_bf16_f32 v100, v69, v71
	v_cvt_pk_bf16_f32 v101, v75, v78
	v_cvt_pk_bf16_f32 v92, v72, v76
	v_cvt_pk_bf16_f32 v93, v79, v93
	v_cvt_pk_bf16_f32 v94, v94, v95
	v_cvt_pk_bf16_f32 v95, v96, v97
	s_waitcnt lgkmcnt(0)
	ds_read_b64_tr_b16 v[102:103], v68 offset:0
	ds_read_b64_tr_b16 v[104:105], v68 offset:0x400
	ds_read_b64_tr_b16 v[106:107], v68 offset:0x800
	ds_read_b64_tr_b16 v[108:109], v68 offset:0xc00
	ds_read_b64_tr_b16 v[110:111], v68 offset:0x200
	ds_read_b64_tr_b16 v[112:113], v68 offset:0x600
	ds_read_b64_tr_b16 v[114:115], v68 offset:0xa00
	ds_read_b64_tr_b16 v[116:117], v68 offset:0xe00
	s_waitcnt lgkmcnt(0)
	s_nop 0
	v_permlane32_swap_b32_e32 v98, v100
	v_permlane32_swap_b32_e32 v99, v101
	v_permlane32_swap_b32_e32 v92, v94
	v_permlane32_swap_b32_e32 v93, v95
	v_mfma_f32_32x32x16_bf16 v[0:15], v[102:105], v[98:101], v[0:15]
	v_mfma_f32_32x32x16_bf16 v[16:31], v[110:113], v[98:101], v[16:31]
	v_mfma_f32_32x32x16_bf16 v[0:15], v[106:109], v[92:95], v[0:15]
	v_mfma_f32_32x32x16_bf16 v[16:31], v[114:117], v[92:95], v[16:31]
	s_waitcnt vmcnt(4)
	ds_write_b128 v149, v[200:203]
	ds_write_b128 v150, v[204:207]
	ds_write_b128 v149, v[208:211] offset:2048
	ds_write_b128 v150, v[212:215] offset:2048
	v_cvt_pk_bf16_f32 v92, v35, v36
	v_cvt_pk_bf16_f32 v93, v37, v38
	v_cvt_pk_bf16_f32 v94, v42, v43
	v_cvt_pk_bf16_f32 v95, v45, v47
	v_cvt_pk_bf16_f32 v42, v44, v46
	v_cvt_pk_bf16_f32 v43, v48, v49
	v_cvt_pk_bf16_f32 v44, v50, v51
	v_cvt_pk_bf16_f32 v45, v147, v148
	s_waitcnt lgkmcnt(0)
	ds_read_b64_tr_b16 v[46:47], v68 offset:0
	ds_read_b64_tr_b16 v[48:49], v68 offset:0x400
	ds_read_b64_tr_b16 v[96:97], v68 offset:0x800
	ds_read_b64_tr_b16 v[98:99], v68 offset:0xc00
	ds_read_b64_tr_b16 v[100:101], v68 offset:0x200
	ds_read_b64_tr_b16 v[102:103], v68 offset:0x600
	ds_read_b64_tr_b16 v[104:105], v68 offset:0xa00
	ds_read_b64_tr_b16 v[106:107], v68 offset:0xe00
	s_waitcnt lgkmcnt(0)
	s_nop 0
	v_permlane32_swap_b32_e32 v92, v94
	v_permlane32_swap_b32_e32 v93, v95
	v_permlane32_swap_b32_e32 v42, v44
	v_permlane32_swap_b32_e32 v43, v45
	v_mfma_f32_32x32x16_bf16 v[0:15], v[46:49], v[92:95], v[0:15]
	v_mfma_f32_32x32x16_bf16 v[16:31], v[100:103], v[92:95], v[16:31]
	v_mfma_f32_32x32x16_bf16 v[0:15], v[96:99], v[42:45], v[0:15]
	v_mfma_f32_32x32x16_bf16 v[16:31], v[104:107], v[42:45], v[16:31]
	s_waitcnt vmcnt(0)
	ds_write_b128 v149, v[216:219]
	ds_write_b128 v150, v[220:223]
	ds_write_b128 v149, v[224:227] offset:2048
	ds_write_b128 v150, v[228:231] offset:2048
	v_cvt_pk_bf16_f32 v36, v52, v53
	v_cvt_pk_bf16_f32 v37, v54, v55
	v_cvt_pk_bf16_f32 v38, v58, v61
	v_cvt_pk_bf16_f32 v39, v63, v66
	v_cvt_pk_bf16_f32 v42, v59, v62
	v_cvt_pk_bf16_f32 v43, v64, v67
	v_cvt_pk_bf16_f32 v44, v70, v73
	v_cvt_pk_bf16_f32 v45, v74, v77
	s_waitcnt lgkmcnt(0)
	ds_read_b64_tr_b16 v[46:47], v68 offset:0
	ds_read_b64_tr_b16 v[48:49], v68 offset:0x400
	ds_read_b64_tr_b16 v[50:51], v68 offset:0x800
	ds_read_b64_tr_b16 v[52:53], v68 offset:0xc00
	ds_read_b64_tr_b16 v[54:55], v68 offset:0x200
	ds_read_b64_tr_b16 v[56:57], v68 offset:0x600
	ds_read_b64_tr_b16 v[58:59], v68 offset:0xa00
	ds_read_b64_tr_b16 v[60:61], v68 offset:0xe00
	s_waitcnt lgkmcnt(0)
	s_nop 0
	v_permlane32_swap_b32_e32 v36, v38
	v_permlane32_swap_b32_e32 v37, v39
	v_permlane32_swap_b32_e32 v42, v44
	v_permlane32_swap_b32_e32 v43, v45
	v_mfma_f32_32x32x16_bf16 v[0:15], v[46:49], v[36:39], v[0:15]
	v_mfma_f32_32x32x16_bf16 v[16:31], v[54:57], v[36:39], v[16:31]
	v_mfma_f32_32x32x16_bf16 v[0:15], v[50:53], v[42:45], v[0:15]
	v_mfma_f32_32x32x16_bf16 v[16:31], v[58:61], v[42:45], v[16:31]
	v_cmp_lt_u32_e32 vcc, 31, v87
	s_and_saveexec_b64 s[4:5], vcc
	s_xor_b64 s[4:5], exec, s[4:5]
	s_ashr_i32 s11, s10, 31
	s_lshl_b64 s[6:7], s[10:11], 15
	s_ashr_i32 s11, s79, 31
	s_add_u32 s6, s6, s79
	s_addc_u32 s7, s7, s11
	s_or_saveexec_b64 s[4:5], s[4:5]
	s_waitcnt lgkmcnt(14)
	v_add_f32_e32 v35, v40, v41
	v_mov_b64_e32 v[32:33], s[6:7]
	s_xor_b64 exec, exec, s[4:5]
	s_cbranch_execz .LBB0_82
; __device__ __forceinline__ void dil_wave_item(const bf16* __restrict__ qkv, bf16* __restrict__ odil, float* __restrict__ lse,
;                               int pat, int g  , int head, char* wl  , const int W) {
;     ...
;   if (hi == 0) lse[((size_t)pat * T + tbase + (i0 + r32) * dil) * 8 + head] = mx + __log2f(ls);
	v_log_f32_e32 v32, v35
	s_ashr_i32 s11, s10, 31
	s_ashr_i32 s66, s79, 31
	s_lshl_b64 s[6:7], s[10:11], 15
	s_add_u32 s6, s6, s79
	s_addc_u32 s7, s7, s66
	v_ashrrev_i32_e32 v87, 31, v86
	v_add_f32_e32 v34, v34, v32
	v_lshl_add_u64 v[32:33], s[6:7], 0, v[86:87]
	v_lshlrev_b64 v[32:33], 5, v[32:33]
	v_lshl_add_u64 v[32:33], s[72:73], 0, v[32:33]
	global_store_dword v[32:33], v34, off
	v_mov_b64_e32 v[32:33], s[6:7]
	s_branch .LBB0_82

; __device__ __forceinline__ void dil_wave_item(const bf16* __restrict__ qkv, bf16* __restrict__ odil, float* __restrict__ lse,
;                               int pat, int g  , int head, char* wl  , const int W) {
;     ...
;   const int dil = (pat == 0) ? 1 : (pat == 1 ? 4 : 16);
;   int seq0, slen, gl;
;   if (g < 256) { seq0 = 0; slen = 8192; gl = g; } else if (g < 512) { seq0 = 8192; slen = 8192; gl = g - 256; } else { seq0 = 16384; slen = 16384; gl = g - 512; }
; __device__ __forceinline__ void attention_phase(const Params& p, int layer, const int W) {
;     ...
;   for (int rep = 0; rep < REP_DIL; ++rep)
;   for (int it = blockIdx.x; it < 3 * 1024; it += gridDim.x) {
;     dil_wave_item(qkv, odil, lse, it / 1024, it % 1024, wid, lds + wid * 4096, W);
.LBB0_294:
	s_and_b32 s98, s27, 0xfffffc00
	s_and_b32 s99, s27, 7
	s_lshl_b32 s99, s99, 7
	s_or_b32 s98, s98, s99
	s_bfe_u32 s99, s27, 0x20008
	s_lshl_b32 s99, s99, 5
	s_or_b32 s98, s98, s99
	s_bfe_u32 s99, s27, 0x50003
	s_or_b32 s98, s98, s99
	s_ashr_i32 s6, s98, 31
	s_lshr_b32 s6, s6, 22
	s_add_i32 s6, s98, s6
	s_ashr_i32 s14, s6, 10
	s_and_b32 s6, s6, 0xfffffc00
	s_sub_i32 s15, s98, s6
	s_cmpk_lt_i32 s15, 0x100
	s_movk_i32 s7, 0x2000
	v_mbcnt_lo_u32_b32 v103, -1, 0
	v_mbcnt_hi_u32_b32 v103, -1, v103
	s_cbranch_scc1 .LBB0_300
	s_lshl_b32 s6, s14, 10
	s_sub_i32 s20, s98, s6
	s_cmpk_gt_u32 s15, 0x1ff
	s_mov_b64 s[6:7], -1
	s_cbranch_scc0 .LBB0_297
	s_add_i32 s15, s20, 0xfffffe00
	s_mov_b64 s[6:7], 0

; __device__ __forceinline__ void dil_wave_item(const bf16* __restrict__ qkv, bf16* __restrict__ odil, float* __restrict__ lse,
;                               int pat, int g  , int head, char* wl  , const int W) {
;     ...
;   const int dil = (pat == 0) ? 1 : (pat == 1 ? 4 : 16);
;   int seq0, slen, gl;
;   if (g < 256) { seq0 = 0; slen = 8192; gl = g; } else if (g < 512) { seq0 = 8192; slen = 8192; gl = g - 256; } else { seq0 = 16384; slen = 16384; gl = g - 512; }
;   const int L = slen / dil, tpr = L / 32, res = gl / tpr, i0 = (gl % tpr) * 32;
;   const int tbase = seq0 + res;
;   bf16x8 qr[4];
;   { const bf16* qp = qkv + (size_t)(tbase + (i0 + r32) * dil) * LDQ + 1536 + head * 64 + hi * 8;
; #pragma unroll
;     for (int d0 = 0; d0 < 4; ++d0) qr[d0] = *reinterpret_cast<const bf16x8*>(qp + d0 * 16); }
;   f32x16 sc[5];
; #pragma unroll
;   for (int kb = 0; kb < 5; ++kb) {
;     int kc = i0 - 64 + kb * 32 + r32; kc = min(max(kc, 0), L - 1);
;     const bf16* kp = qkv + (size_t)(tbase + kc * dil) * LDQ + 2048 + head * 64 + hi * 8;
;     f32x16 a = {};
; #pragma unroll
;     for (int d0 = 0; d0 < 4; ++d0) {
;       bf16x8 kf = *reinterpret_cast<const bf16x8*>(kp + d0 * 16);
;       a = __builtin_amdgcn_mfma_f32_32x32x16_bf16(kf, qr[d0], a, 0, 0, 0);
;     }
;     sc[kb] = a;
;   }
.LBB0_301:
	s_add_i32 s8, s98, 0x3ff
	s_and_b32 s9, s98, 0xfffffc00
	s_cmpk_eq_i32 s9, 0x400
	s_cselect_b32 s9, 2, 4
	s_cmpk_gt_u32 s8, 0x7fe
	s_cselect_b32 s40, s9, 0
	s_lshr_b32 s20, s7, s40
	s_lshr_b32 s7, s20, 5
	s_sext_i32_i16 s9, s7
	v_cvt_f32_i32_e32 v1, s9
	s_sext_i32_i16 s8, s15
	v_cvt_f32_i32_e32 v0, s8
	s_xor_b32 s21, s8, s9
	v_rcp_iflag_f32_e32 v2, v1
	s_ashr_i32 s21, s21, 30
	s_or_b32 s21, s21, 1
	v_and_b32_e32 v102, 31, v103
	v_mul_f32_e32 v2, v0, v2
	v_trunc_f32_e32 v2, v2
	v_fma_f32 v0, -v2, v1, v0
	v_cvt_i32_f32_e32 v2, v2
	v_cmp_ge_f32_e64 s[8:9], |v0|, |v1|
	s_and_b64 s[8:9], s[8:9], exec
	s_cselect_b32 s8, s21, 0
	v_readfirstlane_b32 s9, v2
	s_add_i32 s8, s9, s8
	s_sext_i32_i16 s9, s8
	s_mul_i32 s8, s8, s7
	s_sub_i32 s7, s15, s8
	s_sext_i32_i16 s7, s7
	s_lshl_b32 s41, s7, 5
	v_or_b32_e32 v104, s41, v102
	s_add_i32 s42, s6, s9
	v_lshlrev_b32_e32 v98, s40, v104
	v_bfe_u32 v105, v103, 5, 1
	v_add_u32_e32 v0, s42, v98
	v_mad_i64_i32 v[0:1], s[6:7], v0, s24, v[92:93]
	v_lshlrev_b32_e32 v94, 4, v105
	v_lshl_add_u64 v[4:5], v[0:1], 0, v[94:95]
	v_subrev_u32_e32 v10, 64, v104
	global_load_dwordx4 v[0:3], v[4:5], off offset:3072
	global_load_dwordx4 v[88:91], v[4:5], off offset:3104
	global_load_dwordx4 v[84:87], v[4:5], off offset:3136
	global_load_dwordx4 v[80:83], v[4:5], off offset:3168
	s_add_i32 s15, s20, -1
	v_max_i32_e32 v4, 0, v10
	v_min_u32_e32 v4, s15, v4
	v_lshlrev_b32_e32 v4, s40, v4
	v_add_u32_e32 v4, s42, v4
	v_mad_i64_i32 v[4:5], s[6:7], v4, s24, v[96:97]
	v_lshl_add_u64 v[4:5], v[4:5], 0, s[74:75]
	v_lshl_add_u64 v[4:5], v[4:5], 0, v[94:95]
	v_lshl_add_u64 v[8:9], v[4:5], 0, s[10:11]
	v_add_co_u32_e32 v4, vcc, s25, v4
	v_and_b32_e32 v99, 63, v103
	s_nop 0
	v_addc_co_u32_e32 v5, vcc, 0, v5, vcc
	global_load_dwordx4 v[4:7], v[4:5], off
	s_waitcnt vmcnt(0)
	v_mfma_f32_32x32x16_bf16 v[64:79], v[4:7], v[0:3], 0
	global_load_dwordx4 v[4:7], v[8:9], off offset:32
	s_waitcnt vmcnt(0)
	v_mfma_f32_32x32x16_bf16 v[64:79], v[4:7], v[88:91], v[64:79]
	global_load_dwordx4 v[4:7], v[8:9], off offset:64
	s_waitcnt vmcnt(0)
	v_mfma_f32_32x32x16_bf16 v[64:79], v[4:7], v[84:87], v[64:79]
	global_load_dwordx4 v[4:7], v[8:9], off offset:96
	s_waitcnt vmcnt(0)
	v_mfma_f32_32x32x16_bf16 v[64:79], v[4:7], v[80:83], v[64:79]
	v_max_i32_e32 v4, 0xffffffe0, v10
	v_add_u32_e32 v4, 32, v4
	v_min_u32_e32 v4, s15, v4
	v_lshlrev_b32_e32 v4, s40, v4
	v_add_u32_e32 v4, s42, v4
	v_mad_i64_i32 v[4:5], s[6:7], v4, s24, v[96:97]
	v_lshl_add_u64 v[4:5], v[4:5], 0, s[74:75]
	v_lshl_add_u64 v[4:5], v[4:5], 0, v[94:95]
	v_lshl_add_u64 v[8:9], v[4:5], 0, s[10:11]
	v_add_co_u32_e32 v4, vcc, s25, v4
	s_nop 1
	v_mul_f32_e32 v64, 0x3e38aa3b, v64
	v_addc_co_u32_e32 v5, vcc, 0, v5, vcc
	global_load_dwordx4 v[4:7], v[4:5], off
	v_mul_f32_e32 v65, 0x3e38aa3b, v65
	v_mul_f32_e32 v66, 0x3e38aa3b, v66
	v_mul_f32_e32 v67, 0x3e38aa3b, v67
	s_waitcnt vmcnt(0)
	v_mfma_f32_32x32x16_bf16 v[48:63], v[4:7], v[0:3], 0
	global_load_dwordx4 v[4:7], v[8:9], off offset:32
	s_waitcnt vmcnt(0)
	v_mfma_f32_32x32x16_bf16 v[48:63], v[4:7], v[88:91], v[48:63]
	global_load_dwordx4 v[4:7], v[8:9], off offset:64
	s_waitcnt vmcnt(0)
	v_mfma_f32_32x32x16_bf16 v[48:63], v[4:7], v[84:87], v[48:63]
	global_load_dwordx4 v[4:7], v[8:9], off offset:96
	s_waitcnt vmcnt(0)
	v_mfma_f32_32x32x16_bf16 v[48:63], v[4:7], v[80:83], v[48:63]
	v_max_i32_e32 v4, 0xffffffc0, v10
	v_add_u32_e32 v4, 64, v4
	v_min_u32_e32 v4, s15, v4
	v_lshlrev_b32_e32 v4, s40, v4
	v_add_u32_e32 v4, s42, v4
	v_mad_i64_i32 v[4:5], s[6:7], v4, s24, v[96:97]
	v_lshl_add_u64 v[4:5], v[4:5], 0, s[74:75]
	v_lshl_add_u64 v[4:5], v[4:5], 0, v[94:95]
	v_lshl_add_u64 v[8:9], v[4:5], 0, s[10:11]
	v_add_co_u32_e32 v4, vcc, s25, v4
	s_nop 1
	v_mul_f32_e32 v48, 0x3e38aa3b, v48
	v_addc_co_u32_e32 v5, vcc, 0, v5, vcc
	global_load_dwordx4 v[4:7], v[4:5], off
	v_mul_f32_e32 v49, 0x3e38aa3b, v49
	v_mul_f32_e32 v50, 0x3e38aa3b, v50
	s_waitcnt vmcnt(0)
	v_mfma_f32_32x32x16_bf16 v[32:47], v[4:7], v[0:3], 0
	global_load_dwordx4 v[4:7], v[8:9], off offset:32
	s_waitcnt vmcnt(0)
	v_mfma_f32_32x32x16_bf16 v[32:47], v[4:7], v[88:91], v[32:47]
	global_load_dwordx4 v[4:7], v[8:9], off offset:64
	s_waitcnt vmcnt(0)
	v_mfma_f32_32x32x16_bf16 v[32:47], v[4:7], v[84:87], v[32:47]
	global_load_dwordx4 v[4:7], v[8:9], off offset:96
	s_waitcnt vmcnt(0)
	v_mfma_f32_32x32x16_bf16 v[32:47], v[4:7], v[80:83], v[32:47]
	v_max_i32_e32 v4, 0xffffffa0, v10
	v_add_u32_e32 v4, 0x60, v4
	v_min_u32_e32 v4, s15, v4
	v_lshlrev_b32_e32 v4, s40, v4
	v_add_u32_e32 v4, s42, v4
	v_mad_i64_i32 v[4:5], s[6:7], v4, s24, v[96:97]
	v_lshl_add_u64 v[4:5], v[4:5], 0, s[74:75]
	v_lshl_add_u64 v[4:5], v[4:5], 0, v[94:95]
	v_lshl_add_u64 v[8:9], v[4:5], 0, s[10:11]
	v_add_co_u32_e32 v4, vcc, s25, v4
	s_nop 1
	v_mul_f32_e32 v32, 0x3e38aa3b, v32
	v_addc_co_u32_e32 v5, vcc, 0, v5, vcc
	global_load_dwordx4 v[4:7], v[4:5], off
	v_mul_f32_e32 v33, 0x3e38aa3b, v33
	v_mul_f32_e32 v34, 0x3e38aa3b, v34
	s_waitcnt vmcnt(0)
	v_mfma_f32_32x32x16_bf16 v[16:31], v[4:7], v[0:3], 0
	global_load_dwordx4 v[4:7], v[8:9], off offset:32
	s_waitcnt vmcnt(0)
	v_mfma_f32_32x32x16_bf16 v[16:31], v[4:7], v[88:91], v[16:31]
	global_load_dwordx4 v[4:7], v[8:9], off offset:64
	s_waitcnt vmcnt(0)
	v_mfma_f32_32x32x16_bf16 v[16:31], v[4:7], v[84:87], v[16:31]
	global_load_dwordx4 v[4:7], v[8:9], off offset:96
	s_waitcnt vmcnt(0)
; __device__ __forceinline__ int crow(int r, int hi) { return (r & 3) + 8 * (r >> 2) + 4 * hi; }
; __device__ __forceinline__ void dil_wave_item(const bf16* __restrict__ qkv, bf16* __restrict__ odil, float* __restrict__ lse,
;                               int pat, int g  , int head, char* wl  , const int W) {
;     ...
;   f32x16 sc[5];
; #pragma unroll
;   for (int kb = 0; kb < 5; ++kb) {
;     int kc = i0 - 64 + kb * 32 + r32; kc = min(max(kc, 0), L - 1);
;     const bf16* kp = qkv + (size_t)(tbase + kc * dil) * LDQ + 2048 + head * 64 + hi * 8;
;     f32x16 a = {};
; #pragma unroll
;     for (int d0 = 0; d0 < 4; ++d0) {
;       bf16x8 kf = *reinterpret_cast<const bf16x8*>(kp + d0 * 16);
;       a = __builtin_amdgcn_mfma_f32_32x32x16_bf16(kf, qr[d0], a, 0, 0, 0);
;     }
;     sc[kb] = a;
;   }
;   float mx = -1e30f;
; #pragma unroll
;   for (int kb = 0; kb < 5; ++kb)
; #pragma unroll
;     for (int r = 0; r < 16; ++r) {
;       const int rel = kb * 32 - 64 + crow(r, hi) - r32;
;       const int kc = i0 + r32 + rel;
;       const bool ok = (rel >= -64) && (rel <= 64) && (kc >= 0) && (kc < L);
;       const float s = ok ? sc[kb][r] * AC : -1e30f;
;       sc[kb][r] = s; mx = fmaxf(mx, s);
;     }
	v_mfma_f32_32x32x16_bf16 v[16:31], v[4:7], v[80:83], v[16:31]
	v_max_i32_e32 v4, 0xffffff80, v10
	v_add_u32_e32 v4, 0x80, v4
	v_min_u32_e32 v4, s15, v4
	v_lshlrev_b32_e32 v4, s40, v4
	v_add_u32_e32 v4, s42, v4
	v_mad_i64_i32 v[4:5], s[6:7], v4, s24, v[96:97]
	v_lshl_add_u64 v[4:5], v[4:5], 0, s[74:75]
	v_lshl_add_u64 v[4:5], v[4:5], 0, v[94:95]
	v_lshl_add_u64 v[110:111], v[4:5], 0, s[10:11]
	v_add_co_u32_e32 v4, vcc, s25, v4
	global_load_dwordx4 v[106:109], v[110:111], off offset:32
	s_nop 0
	v_addc_co_u32_e32 v5, vcc, 0, v5, vcc
	global_load_dwordx4 v[4:7], v[4:5], off
	v_mul_f32_e32 v16, 0x3e38aa3b, v16
	s_waitcnt vmcnt(0)
	v_mfma_f32_32x32x16_bf16 v[0:15], v[4:7], v[0:3], 0
	v_mfma_f32_32x32x16_bf16 v[0:15], v[106:109], v[88:91], v[0:15]
	global_load_dwordx4 v[88:91], v[110:111], off offset:64
	s_waitcnt vmcnt(0)
	v_mfma_f32_32x32x16_bf16 v[0:15], v[88:91], v[84:87], v[0:15]
	global_load_dwordx4 v[84:87], v[110:111], off offset:96
	s_waitcnt vmcnt(0)
	v_mfma_f32_32x32x16_bf16 v[0:15], v[84:87], v[80:83], v[0:15]
	v_lshlrev_b32_e32 v80, 2, v105
	v_sub_u32_e32 v81, v80, v102
	v_add_u32_e32 v82, v104, v81
	v_subrev_u32_e32 v83, 64, v82
	v_cmp_gt_u32_e32 vcc, s26, v81
	v_cmp_gt_u32_e64 s[6:7], s20, v83
	s_and_b64 vcc, vcc, s[6:7]
	v_subrev_u32_e32 v83, 63, v82
	v_add_u32_e32 v86, 1, v81
	v_cndmask_b32_e32 v64, v101, v64, vcc
	v_cmp_gt_u32_e32 vcc, s26, v86
	v_cmp_gt_u32_e64 s[6:7], s20, v83
	s_and_b64 vcc, vcc, s[6:7]
	v_cndmask_b32_e32 v65, v101, v65, vcc
	s_mov_b32 s6, 0xf149f2ca
	v_subrev_u32_e32 v83, 62, v82
	v_add_u32_e32 v87, 2, v81
	v_max3_f32 v84, v64, s6, v65
	v_cmp_gt_u32_e32 vcc, s26, v87
	v_cmp_gt_u32_e64 s[6:7], s20, v83
	s_and_b64 vcc, vcc, s[6:7]
	v_subrev_u32_e32 v83, 61, v82
	v_add_u32_e32 v88, 3, v81
	v_cndmask_b32_e32 v66, v101, v66, vcc
	v_cmp_gt_u32_e32 vcc, s26, v88
	v_cmp_gt_u32_e64 s[6:7], s20, v83
	s_and_b64 vcc, vcc, s[6:7]
	v_cndmask_b32_e32 v83, v101, v67, vcc
	v_subrev_u32_e32 v67, 56, v82
	v_add_u32_e32 v89, 8, v81
	v_cmp_gt_u32_e32 vcc, s26, v89
	v_cmp_gt_u32_e64 s[6:7], s20, v67
	s_and_b64 vcc, vcc, s[6:7]
	v_mul_f32_e32 v67, 0x3e38aa3b, v68
	v_subrev_u32_e32 v68, 55, v82
	v_add_u32_e32 v90, 9, v81
	v_cndmask_b32_e32 v67, v101, v67, vcc
	v_cmp_gt_u32_e32 vcc, s26, v90
	v_cmp_gt_u32_e64 s[6:7], s20, v68
	s_and_b64 vcc, vcc, s[6:7]
	v_mul_f32_e32 v68, 0x3e38aa3b, v69
	v_subrev_u32_e32 v69, 54, v82
	v_add_u32_e32 v91, 10, v81
	v_cndmask_b32_e32 v68, v101, v68, vcc
	v_cmp_gt_u32_e32 vcc, s26, v91
	v_cmp_gt_u32_e64 s[6:7], s20, v69
	s_and_b64 vcc, vcc, s[6:7]
	v_mul_f32_e32 v69, 0x3e38aa3b, v70
	v_subrev_u32_e32 v70, 53, v82
	v_add_u32_e32 v105, 11, v81
	v_cndmask_b32_e32 v69, v101, v69, vcc
	v_cmp_gt_u32_e32 vcc, s26, v105
	v_cmp_gt_u32_e64 s[6:7], s20, v70
	s_and_b64 vcc, vcc, s[6:7]
	v_mul_f32_e32 v70, 0x3e38aa3b, v71
	v_cndmask_b32_e32 v71, v101, v70, vcc
	v_subrev_u32_e32 v70, 48, v82
	v_add_u32_e32 v106, 16, v81
	v_cmp_gt_u32_e32 vcc, s26, v106
	v_cmp_gt_u32_e64 s[6:7], s20, v70
	s_and_b64 vcc, vcc, s[6:7]
	v_mul_f32_e32 v70, 0x3e38aa3b, v72
	v_subrev_u32_e32 v72, 47, v82
	v_add_u32_e32 v107, 17, v81
	v_cndmask_b32_e32 v70, v101, v70, vcc
	v_cmp_gt_u32_e32 vcc, s26, v107
	v_cmp_gt_u32_e64 s[6:7], s20, v72
	s_and_b64 vcc, vcc, s[6:7]
	v_mul_f32_e32 v72, 0x3e38aa3b, v73
	v_subrev_u32_e32 v73, 46, v82
	v_add_u32_e32 v108, 18, v81
	v_cndmask_b32_e32 v72, v101, v72, vcc
	v_cmp_gt_u32_e32 vcc, s26, v108
	v_cmp_gt_u32_e64 s[6:7], s20, v73
	s_and_b64 vcc, vcc, s[6:7]
	v_mul_f32_e32 v73, 0x3e38aa3b, v74
	v_subrev_u32_e32 v74, 45, v82
	v_add_u32_e32 v109, 19, v81
	v_cndmask_b32_e32 v73, v101, v73, vcc
	v_cmp_gt_u32_e32 vcc, s26, v109
	v_cmp_gt_u32_e64 s[6:7], s20, v74
	s_and_b64 vcc, vcc, s[6:7]
	v_mul_f32_e32 v74, 0x3e38aa3b, v75
	v_cndmask_b32_e32 v75, v101, v74, vcc
	v_subrev_u32_e32 v74, 40, v82
	v_add_u32_e32 v110, 24, v81
	v_cmp_gt_u32_e32 vcc, s26, v110
	v_cmp_gt_u32_e64 s[6:7], s20, v74
	s_and_b64 vcc, vcc, s[6:7]
	v_mul_f32_e32 v74, 0x3e38aa3b, v76
	v_subrev_u32_e32 v76, 39, v82
	v_add_u32_e32 v111, 25, v81
	v_cndmask_b32_e32 v74, v101, v74, vcc
	v_cmp_gt_u32_e32 vcc, s26, v111
	v_cmp_gt_u32_e64 s[6:7], s20, v76
	v_max3_f32 v84, v84, v66, v83
	s_and_b64 vcc, vcc, s[6:7]
	v_mul_f32_e32 v76, 0x3e38aa3b, v77
	v_subrev_u32_e32 v77, 38, v82
	v_add_u32_e32 v112, 26, v81
	v_max3_f32 v84, v84, v67, v68
	v_cndmask_b32_e32 v76, v101, v76, vcc
	v_cmp_gt_u32_e32 vcc, s26, v112
	v_cmp_gt_u32_e64 s[6:7], s20, v77
	v_max3_f32 v84, v84, v69, v71
	s_and_b64 vcc, vcc, s[6:7]
	v_mul_f32_e32 v77, 0x3e38aa3b, v78
	v_subrev_u32_e32 v78, 37, v82
	v_add_u32_e32 v113, 27, v81
	v_max3_f32 v84, v84, v70, v72
	v_cndmask_b32_e32 v77, v101, v77, vcc
	v_cmp_gt_u32_e32 vcc, s26, v113
	v_cmp_gt_u32_e64 s[6:7], s20, v78
	v_max3_f32 v84, v84, v73, v75
	s_and_b64 vcc, vcc, s[6:7]
	v_mul_f32_e32 v78, 0x3e38aa3b, v79
	v_max3_f32 v84, v84, v74, v76
	v_cndmask_b32_e32 v78, v101, v78, vcc
	v_max3_f32 v79, v84, v77, v78
	v_subrev_u32_e32 v84, 32, v82
	v_cmp_gt_u32_e32 vcc, s20, v84
	v_subrev_u32_e32 v84, 31, v82
	v_mul_f32_e32 v0, 0x3e38aa3b, v0
	v_cndmask_b32_e32 v48, v101, v48, vcc
	v_cmp_gt_u32_e32 vcc, s20, v84
	v_mul_f32_e32 v1, 0x3e38aa3b, v1
	v_mul_f32_e32 v2, 0x3e38aa3b, v2
	v_cndmask_b32_e32 v49, v101, v49, vcc
	v_max3_f32 v85, v79, v48, v49
	v_subrev_u32_e32 v79, 30, v82
	v_cmp_gt_u32_e32 vcc, s20, v79
	v_mul_f32_e32 v3, 0x3e38aa3b, v3
	v_mul_f32_e32 v4, 0x3e38aa3b, v4
	v_cndmask_b32_e32 v79, v101, v50, vcc
	v_subrev_u32_e32 v50, 29, v82
	v_cmp_gt_u32_e32 vcc, s20, v50
	v_mul_f32_e32 v50, 0x3e38aa3b, v51
	v_subrev_u32_e32 v51, 23, v82
	v_cndmask_b32_e32 v84, v101, v50, vcc
	v_subrev_u32_e32 v50, 24, v82
	v_cmp_gt_u32_e32 vcc, s20, v50
; __device__ __forceinline__ int crow(int r, int hi) { return (r & 3) + 8 * (r >> 2) + 4 * hi; }
; __device__ __forceinline__ void dil_wave_item(const bf16* __restrict__ qkv, bf16* __restrict__ odil, float* __restrict__ lse,
;                               int pat, int g  , int head, char* wl  , const int W) {
;     ...
;   float mx = -1e30f;
; #pragma unroll
;   for (int kb = 0; kb < 5; ++kb)
; #pragma unroll
;     for (int r = 0; r < 16; ++r) {
;       const int rel = kb * 32 - 64 + crow(r, hi) - r32;
;       const int kc = i0 + r32 + rel;
;       const bool ok = (rel >= -64) && (rel <= 64) && (kc >= 0) && (kc < L);
;       const float s = ok ? sc[kb][r] * AC : -1e30f;
;       sc[kb][r] = s; mx = fmaxf(mx, s);
;     }
	v_mul_f32_e32 v50, 0x3e38aa3b, v52
	v_max3_f32 v85, v85, v79, v84
	v_cndmask_b32_e32 v50, v101, v50, vcc
	v_cmp_gt_u32_e32 vcc, s20, v51
	v_mul_f32_e32 v51, 0x3e38aa3b, v53
	v_subrev_u32_e32 v53, 22, v82
	v_cndmask_b32_e32 v51, v101, v51, vcc
	v_cmp_gt_u32_e32 vcc, s20, v53
	v_mul_f32_e32 v53, 0x3e38aa3b, v54
	v_subrev_u32_e32 v54, 21, v82
	v_cndmask_b32_e32 v53, v101, v53, vcc
	v_cmp_gt_u32_e32 vcc, s20, v54
	v_mul_f32_e32 v54, 0x3e38aa3b, v55
	v_max3_f32 v52, v85, v50, v51
	v_cndmask_b32_e32 v85, v101, v54, vcc
	v_max3_f32 v55, v52, v53, v85
	v_add_u32_e32 v52, -16, v82
	v_cmp_gt_u32_e32 vcc, s20, v52
	v_mul_f32_e32 v52, 0x3e38aa3b, v56
	v_add_u32_e32 v54, -15, v82
	v_cndmask_b32_e32 v52, v101, v52, vcc
	v_cmp_gt_u32_e32 vcc, s20, v54
	v_mul_f32_e32 v54, 0x3e38aa3b, v57
	v_add_u32_e32 v56, -14, v82
	v_cndmask_b32_e32 v54, v101, v54, vcc
	v_cmp_gt_u32_e32 vcc, s20, v56
	v_mul_f32_e32 v56, 0x3e38aa3b, v58
	v_add_u32_e32 v58, -7, v82
	v_cndmask_b32_e32 v57, v101, v56, vcc
	v_add_u32_e32 v56, -13, v82
	v_cmp_gt_u32_e32 vcc, s20, v56
	v_mul_f32_e32 v56, 0x3e38aa3b, v59
	v_max3_f32 v55, v55, v52, v54
	v_cndmask_b32_e32 v59, v101, v56, vcc
	v_add_u32_e32 v56, -8, v82
	v_cmp_gt_u32_e32 vcc, s20, v56
	v_mul_f32_e32 v56, 0x3e38aa3b, v60
	v_add_u32_e32 v60, -6, v82
	v_cndmask_b32_e32 v56, v101, v56, vcc
	v_cmp_gt_u32_e32 vcc, s20, v58
	v_mul_f32_e32 v58, 0x3e38aa3b, v61
	v_add_u32_e32 v61, -5, v82
	v_cndmask_b32_e32 v58, v101, v58, vcc
	v_cmp_gt_u32_e32 vcc, s20, v60
	v_mul_f32_e32 v60, 0x3e38aa3b, v62
	v_add_u32_e32 v62, v104, v86
	v_cndmask_b32_e32 v60, v101, v60, vcc
	v_cmp_gt_u32_e32 vcc, s20, v61
	v_mul_f32_e32 v61, 0x3e38aa3b, v63
	v_max3_f32 v55, v55, v57, v59
	v_cndmask_b32_e32 v61, v101, v61, vcc
	v_cmp_gt_u32_e32 vcc, s20, v82
	v_max3_f32 v55, v55, v56, v58
	v_max3_f32 v55, v55, v60, v61
	v_cndmask_b32_e32 v32, v101, v32, vcc
	v_cmp_gt_u32_e32 vcc, s20, v62
	v_add_u32_e32 v62, v104, v87
	v_mul_f32_e32 v5, 0x3e38aa3b, v5
	v_cndmask_b32_e32 v33, v101, v33, vcc
	v_cmp_gt_u32_e32 vcc, s20, v62
	v_max3_f32 v55, v55, v32, v33
	v_mul_f32_e32 v6, 0x3e38aa3b, v6
	v_cndmask_b32_e32 v62, v101, v34, vcc
	v_add_u32_e32 v34, v104, v88
	v_cmp_gt_u32_e32 vcc, s20, v34
	v_mul_f32_e32 v34, 0x3e38aa3b, v35
	v_add_u32_e32 v35, v104, v89
	v_cndmask_b32_e32 v63, v101, v34, vcc
	v_cmp_gt_u32_e32 vcc, s20, v35
	v_mul_f32_e32 v35, 0x3e38aa3b, v36
	v_add_u32_e32 v36, v104, v90
	v_cndmask_b32_e32 v35, v101, v35, vcc
	v_cmp_gt_u32_e32 vcc, s20, v36
	v_mul_f32_e32 v36, 0x3e38aa3b, v37
	v_add_u32_e32 v37, v104, v91
	v_cndmask_b32_e32 v36, v101, v36, vcc
	v_cmp_gt_u32_e32 vcc, s20, v37
	v_mul_f32_e32 v37, 0x3e38aa3b, v38
	v_max3_f32 v34, v55, v62, v63
	v_cndmask_b32_e32 v88, v101, v37, vcc
	v_add_u32_e32 v37, v104, v105
	v_cmp_gt_u32_e32 vcc, s20, v37
	v_mul_f32_e32 v37, 0x3e38aa3b, v39
	v_max3_f32 v34, v34, v35, v36
	v_cndmask_b32_e32 v105, v101, v37, vcc
	v_add_u32_e32 v37, v104, v106
	v_cmp_gt_u32_e32 vcc, s20, v37
	v_mul_f32_e32 v37, 0x3e38aa3b, v40
	v_max3_f32 v34, v34, v88, v105
	v_cndmask_b32_e32 v87, v101, v37, vcc
	v_add_u32_e32 v37, v104, v107
	v_cmp_gt_u32_e32 vcc, s20, v37
	v_mul_f32_e32 v37, 0x3e38aa3b, v41
	v_mul_f32_e32 v7, 0x3e38aa3b, v7
	v_cndmask_b32_e32 v90, v101, v37, vcc
	v_add_u32_e32 v37, v104, v108
	v_cmp_gt_u32_e32 vcc, s20, v37
	v_mul_f32_e32 v37, 0x3e38aa3b, v42
	v_max3_f32 v34, v34, v87, v90
	v_cndmask_b32_e32 v108, v101, v37, vcc
	v_add_u32_e32 v37, v104, v109
	v_cmp_gt_u32_e32 vcc, s20, v37
	v_mul_f32_e32 v37, 0x3e38aa3b, v43
	v_mul_f32_e32 v8, 0x3e38aa3b, v8
	v_cndmask_b32_e32 v109, v101, v37, vcc
	v_add_u32_e32 v37, v104, v110
	v_cmp_gt_u32_e32 vcc, s20, v37
	v_mul_f32_e32 v37, 0x3e38aa3b, v44
	v_max3_f32 v34, v34, v108, v109
	v_cndmask_b32_e32 v107, v101, v37, vcc
	v_add_u32_e32 v37, v104, v111
	v_cmp_gt_u32_e32 vcc, s20, v37
	v_mul_f32_e32 v37, 0x3e38aa3b, v45
	v_mul_f32_e32 v9, 0x3e38aa3b, v9
	v_cndmask_b32_e32 v45, v101, v37, vcc
	v_add_u32_e32 v37, v104, v112
	v_cmp_gt_u32_e32 vcc, s20, v37
	v_mul_f32_e32 v37, 0x3e38aa3b, v46
	v_max3_f32 v34, v34, v107, v45
	v_cndmask_b32_e32 v110, v101, v37, vcc
	v_add_u32_e32 v37, v104, v113
	v_cmp_gt_u32_e32 vcc, s20, v37
	v_mul_f32_e32 v37, 0x3e38aa3b, v47
	v_mul_f32_e32 v10, 0x3e38aa3b, v10
	v_cndmask_b32_e32 v111, v101, v37, vcc
	v_add_u32_e32 v37, 32, v82
	v_cmp_gt_u32_e32 vcc, s20, v37
	v_max3_f32 v34, v34, v110, v111
	v_mul_f32_e32 v11, 0x3e38aa3b, v11
	v_cndmask_b32_e32 v46, v101, v16, vcc
	v_add_u32_e32 v16, 33, v82
	v_cmp_gt_u32_e32 vcc, s20, v16
	v_mul_f32_e32 v16, 0x3e38aa3b, v17
	v_add_u32_e32 v17, 34, v82
	v_cndmask_b32_e32 v104, v101, v16, vcc
	v_cmp_gt_u32_e32 vcc, s20, v17
	v_mul_f32_e32 v17, 0x3e38aa3b, v18
	v_add_u32_e32 v18, 0x80, v81
	v_cndmask_b32_e32 v113, v101, v17, vcc
	v_add_u32_e32 v17, 35, v82
	v_cmp_gt_u32_e32 vcc, s20, v17
	v_mul_f32_e32 v17, 0x3e38aa3b, v19
	v_max3_f32 v16, v34, v46, v104
	v_cndmask_b32_e32 v115, v101, v17, vcc
	v_add_u32_e32 v17, 40, v82
	v_cmp_gt_u32_e32 vcc, s20, v17
	v_mul_f32_e32 v17, 0x3e38aa3b, v20
	v_max3_f32 v16, v16, v113, v115
	v_cndmask_b32_e32 v112, v101, v17, vcc
	v_add_u32_e32 v17, 41, v82
	v_cmp_gt_u32_e32 vcc, s20, v17
	v_mul_f32_e32 v17, 0x3e38aa3b, v21
	v_mul_f32_e32 v12, 0x3e38aa3b, v12
	v_cndmask_b32_e32 v114, v101, v17, vcc
	v_add_u32_e32 v17, 42, v82
	v_cmp_gt_u32_e32 vcc, s20, v17
	v_mul_f32_e32 v17, 0x3e38aa3b, v22
	v_max3_f32 v16, v16, v112, v114
	v_cndmask_b32_e32 v117, v101, v17, vcc
	v_add_u32_e32 v17, 43, v82
	v_cmp_gt_u32_e32 vcc, s20, v17
	v_mul_f32_e32 v17, 0x3e38aa3b, v23
	v_mul_f32_e32 v13, 0x3e38aa3b, v13
	v_cndmask_b32_e32 v119, v101, v17, vcc
	v_add_u32_e32 v17, 48, v82
	v_cmp_gt_u32_e32 vcc, s20, v17
; __device__ __forceinline__ float shfl_idx(float v, int srclane) { return __int_as_float(__builtin_amdgcn_ds_bpermute(srclane << 2, __float_as_int(v))); }
; __device__ __forceinline__ int crow(int r, int hi) { return (r & 3) + 8 * (r >> 2) + 4 * hi; }
; __device__ __forceinline__ void dil_wave_item(const bf16* __restrict__ qkv, bf16* __restrict__ odil, float* __restrict__ lse,
;                               int pat, int g  , int head, char* wl  , const int W) {
;     ...
;   float mx = -1e30f;
; #pragma unroll
;   for (int kb = 0; kb < 5; ++kb)
; #pragma unroll
;     for (int r = 0; r < 16; ++r) {
;       const int rel = kb * 32 - 64 + crow(r, hi) - r32;
;       const int kc = i0 + r32 + rel;
;       const bool ok = (rel >= -64) && (rel <= 64) && (kc >= 0) && (kc < L);
;       const float s = ok ? sc[kb][r] * AC : -1e30f;
;       sc[kb][r] = s; mx = fmaxf(mx, s);
;     }
;   mx = fmaxf(mx, shfl_idx(mx, lane ^ 32));
	v_mul_f32_e32 v17, 0x3e38aa3b, v24
	v_max3_f32 v16, v16, v117, v119
	v_cndmask_b32_e32 v116, v101, v17, vcc
	v_add_u32_e32 v17, 49, v82
	v_cmp_gt_u32_e32 vcc, s20, v17
	v_mul_f32_e32 v17, 0x3e38aa3b, v25
	v_mul_f32_e32 v14, 0x3e38aa3b, v14
	v_cndmask_b32_e32 v118, v101, v17, vcc
	v_add_u32_e32 v17, 50, v82
	v_cmp_gt_u32_e32 vcc, s20, v17
	v_mul_f32_e32 v17, 0x3e38aa3b, v26
	v_max3_f32 v16, v16, v116, v118
	v_cndmask_b32_e32 v121, v101, v17, vcc
	v_add_u32_e32 v17, 51, v82
	v_cmp_gt_u32_e32 vcc, s20, v17
	v_mul_f32_e32 v17, 0x3e38aa3b, v27
	v_mul_f32_e32 v15, 0x3e38aa3b, v15
	v_cndmask_b32_e32 v123, v101, v17, vcc
	v_add_u32_e32 v17, 56, v82
	v_cmp_gt_u32_e32 vcc, s20, v17
	v_mul_f32_e32 v17, 0x3e38aa3b, v28
	v_max3_f32 v16, v16, v121, v123
	v_cndmask_b32_e32 v120, v101, v17, vcc
	v_add_u32_e32 v17, 57, v82
	v_cmp_gt_u32_e32 vcc, s20, v17
	v_mul_f32_e32 v17, 0x3e38aa3b, v29
	s_nop 0
	v_cndmask_b32_e32 v122, v101, v17, vcc
	v_add_u32_e32 v17, 58, v82
	v_cmp_gt_u32_e32 vcc, s20, v17
	v_mul_f32_e32 v17, 0x3e38aa3b, v30
	v_max3_f32 v16, v16, v120, v122
	v_cndmask_b32_e32 v124, v101, v17, vcc
	v_add_u32_e32 v17, 59, v82
	v_cmp_gt_u32_e32 vcc, s20, v17
	v_mul_f32_e32 v17, 0x3e38aa3b, v31
	s_nop 0
	v_cndmask_b32_e32 v125, v101, v17, vcc
	v_add_u32_e32 v17, 64, v82
	v_cmp_gt_u32_e32 vcc, s26, v18
	v_cmp_gt_u32_e64 s[6:7], s20, v17
	s_and_b64 vcc, vcc, s[6:7]
	v_add_u32_e32 v17, 0x41, v82
	s_movk_i32 s6, 0xff7e
	v_cndmask_b32_e32 v0, v101, v0, vcc
	v_cmp_lt_u32_e32 vcc, s6, v81
	v_cmp_gt_u32_e64 s[6:7], s20, v17
	s_and_b64 vcc, vcc, s[6:7]
	v_add_u32_e32 v17, 0x42, v82
	v_add_u32_e32 v18, 0x82, v81
	v_cndmask_b32_e32 v1, v101, v1, vcc
	v_cmp_gt_u32_e32 vcc, s26, v18
	v_cmp_gt_u32_e64 s[6:7], s20, v17
	s_and_b64 vcc, vcc, s[6:7]
	v_add_u32_e32 v17, 0x43, v82
	v_add_u32_e32 v18, 0x83, v81
	v_cndmask_b32_e32 v2, v101, v2, vcc
	v_cmp_gt_u32_e32 vcc, s26, v18
	v_cmp_gt_u32_e64 s[6:7], s20, v17
	s_and_b64 vcc, vcc, s[6:7]
	v_add_u32_e32 v17, 0x48, v82
	v_add_u32_e32 v18, 0x88, v81
	v_cndmask_b32_e32 v3, v101, v3, vcc
	v_cmp_gt_u32_e32 vcc, s26, v18
	v_cmp_gt_u32_e64 s[6:7], s20, v17
	s_and_b64 vcc, vcc, s[6:7]
	v_add_u32_e32 v17, 0x49, v82
	v_add_u32_e32 v18, 0x89, v81
	v_cndmask_b32_e32 v4, v101, v4, vcc
	v_cmp_gt_u32_e32 vcc, s26, v18
	v_cmp_gt_u32_e64 s[6:7], s20, v17
	s_and_b64 vcc, vcc, s[6:7]
	v_add_u32_e32 v17, 0x4a, v82
	v_add_u32_e32 v18, 0x8a, v81
	v_cndmask_b32_e32 v5, v101, v5, vcc
	v_cmp_gt_u32_e32 vcc, s26, v18
	v_cmp_gt_u32_e64 s[6:7], s20, v17
	s_and_b64 vcc, vcc, s[6:7]
	v_add_u32_e32 v17, 0x4b, v82
	v_add_u32_e32 v18, 0x8b, v81
	v_cndmask_b32_e32 v6, v101, v6, vcc
	v_cmp_gt_u32_e32 vcc, s26, v18
	v_cmp_gt_u32_e64 s[6:7], s20, v17
	s_and_b64 vcc, vcc, s[6:7]
	v_add_u32_e32 v17, 0x50, v82
	v_add_u32_e32 v18, 0x90, v81
	v_cndmask_b32_e32 v7, v101, v7, vcc
	v_cmp_gt_u32_e32 vcc, s26, v18
	v_cmp_gt_u32_e64 s[6:7], s20, v17
	s_and_b64 vcc, vcc, s[6:7]
	v_add_u32_e32 v17, 0x51, v82
	v_add_u32_e32 v18, 0x91, v81
	v_cndmask_b32_e32 v8, v101, v8, vcc
	v_cmp_gt_u32_e32 vcc, s26, v18
	v_cmp_gt_u32_e64 s[6:7], s20, v17
	s_and_b64 vcc, vcc, s[6:7]
	v_add_u32_e32 v17, 0x52, v82
	v_add_u32_e32 v18, 0x92, v81
	v_cndmask_b32_e32 v9, v101, v9, vcc
	v_cmp_gt_u32_e32 vcc, s26, v18
	v_cmp_gt_u32_e64 s[6:7], s20, v17
	s_and_b64 vcc, vcc, s[6:7]
	v_add_u32_e32 v17, 0x53, v82
	v_add_u32_e32 v18, 0x93, v81
	v_cndmask_b32_e32 v10, v101, v10, vcc
	v_cmp_gt_u32_e32 vcc, s26, v18
	v_cmp_gt_u32_e64 s[6:7], s20, v17
	s_and_b64 vcc, vcc, s[6:7]
	v_add_u32_e32 v17, 0x58, v82
	v_add_u32_e32 v18, 0x98, v81
	v_cndmask_b32_e32 v11, v101, v11, vcc
	v_cmp_gt_u32_e32 vcc, s26, v18
	v_cmp_gt_u32_e64 s[6:7], s20, v17
	v_max3_f32 v16, v16, v124, v125
	s_and_b64 vcc, vcc, s[6:7]
	v_add_u32_e32 v17, 0x59, v82
	v_add_u32_e32 v18, 0x99, v81
	v_max3_f32 v16, v16, v0, v1
	v_cndmask_b32_e32 v12, v101, v12, vcc
	v_cmp_gt_u32_e32 vcc, s26, v18
	v_cmp_gt_u32_e64 s[6:7], s20, v17
	v_max3_f32 v16, v16, v2, v3
	s_and_b64 vcc, vcc, s[6:7]
	v_add_u32_e32 v17, 0x5a, v82
	v_add_u32_e32 v18, 0x9a, v81
	v_max3_f32 v16, v16, v4, v5
	v_cndmask_b32_e32 v13, v101, v13, vcc
	v_cmp_gt_u32_e32 vcc, s26, v18
	v_cmp_gt_u32_e64 s[6:7], s20, v17
	v_max3_f32 v16, v16, v6, v7
	s_and_b64 vcc, vcc, s[6:7]
	v_add_u32_e32 v17, 0x5b, v82
	v_add_u32_e32 v18, 0x9b, v81
	v_max3_f32 v16, v16, v8, v9
	v_cndmask_b32_e32 v14, v101, v14, vcc
	v_cmp_gt_u32_e32 vcc, s26, v18
	v_cmp_gt_u32_e64 s[6:7], s20, v17
	v_max3_f32 v16, v16, v10, v11
	s_and_b64 vcc, vcc, s[6:7]
	v_max3_f32 v16, v16, v12, v13
	v_cndmask_b32_e32 v15, v101, v15, vcc
	v_lshlrev_b32_e32 v17, 2, v99
	v_max3_f32 v16, v16, v14, v15
	v_xor_b32_e32 v126, 0x80, v17
	ds_bpermute_b32 v17, v126, v16
	s_waitcnt lgkmcnt(0)
; __device__ __forceinline__ float shfl_idx(float v, int srclane) { return __int_as_float(__builtin_amdgcn_ds_bpermute(srclane << 2, __float_as_int(v))); }
; __device__ __forceinline__ void dil_wave_item(const bf16* __restrict__ qkv, bf16* __restrict__ odil, float* __restrict__ lse,
;                               int pat, int g  , int head, char* wl  , const int W) {
;     ...
;   mx = fmaxf(mx, shfl_idx(mx, lane ^ 32));
;   float ls = 0.f;
; #pragma unroll
;   for (int kb = 0; kb < 5; ++kb)
; #pragma unroll
;     for (int r = 0; r < 16; ++r) { const float e = __builtin_amdgcn_exp2f(sc[kb][r] - mx); sc[kb][r] = e; ls += e; }
;   ls += shfl_idx(ls, lane ^ 32);
	v_max_f32_e32 v17, v17, v17
	v_max_f32_e32 v34, v16, v17
	v_sub_f32_e32 v16, v64, v34
	v_exp_f32_e32 v16, v16
	v_sub_f32_e32 v17, v65, v34
	v_exp_f32_e32 v17, v17
	v_sub_f32_e32 v41, v84, v34
	v_add_f32_e32 v18, 0, v16
	v_exp_f32_e32 v41, v41
	v_add_f32_e32 v19, v17, v18
	v_sub_f32_e32 v18, v66, v34
	v_exp_f32_e32 v18, v18
	v_sub_f32_e32 v42, v50, v34
	v_exp_f32_e32 v44, v42
	v_sub_f32_e32 v42, v51, v34
	v_add_f32_e32 v20, v18, v19
	v_sub_f32_e32 v19, v83, v34
	v_exp_f32_e32 v19, v19
	v_exp_f32_e32 v50, v42
	v_sub_f32_e32 v42, v53, v34
	v_exp_f32_e32 v55, v42
	v_add_f32_e32 v21, v19, v20
	v_sub_f32_e32 v20, v67, v34
	v_exp_f32_e32 v20, v20
	v_sub_f32_e32 v42, v85, v34
	v_exp_f32_e32 v65, v42
	v_sub_f32_e32 v42, v52, v34
	v_add_f32_e32 v22, v20, v21
	v_sub_f32_e32 v21, v68, v34
	v_exp_f32_e32 v21, v21
	v_exp_f32_e32 v68, v42
	v_sub_f32_e32 v42, v54, v34
	v_sub_f32_e32 v32, v32, v34
	v_add_f32_e32 v23, v21, v22
	v_sub_f32_e32 v22, v69, v34
	v_exp_f32_e32 v22, v22
	v_sub_f32_e32 v33, v33, v34
	v_sub_f32_e32 v0, v0, v34
	v_sub_f32_e32 v1, v1, v34
	v_add_f32_e32 v24, v22, v23
	v_sub_f32_e32 v23, v71, v34
	v_exp_f32_e32 v23, v23
	s_nop 0
	v_add_f32_e32 v25, v23, v24
	v_sub_f32_e32 v24, v70, v34
	v_exp_f32_e32 v24, v24
	s_nop 0
	v_add_f32_e32 v26, v24, v25
	v_sub_f32_e32 v25, v72, v34
	v_exp_f32_e32 v25, v25
	s_nop 0
	v_add_f32_e32 v27, v25, v26
	v_sub_f32_e32 v26, v73, v34
	v_exp_f32_e32 v26, v26
	v_exp_f32_e32 v73, v42
	v_sub_f32_e32 v42, v57, v34
	v_add_f32_e32 v28, v26, v27
	v_sub_f32_e32 v27, v75, v34
	v_exp_f32_e32 v27, v27
	s_nop 0
	v_add_f32_e32 v29, v27, v28
	v_sub_f32_e32 v28, v74, v34
	v_exp_f32_e32 v28, v28
	s_nop 0
	v_add_f32_e32 v30, v28, v29
	v_sub_f32_e32 v29, v76, v34
	v_exp_f32_e32 v29, v29
	v_exp_f32_e32 v76, v42
	v_sub_f32_e32 v42, v59, v34
	v_exp_f32_e32 v81, v42
	v_add_f32_e32 v31, v29, v30
	v_sub_f32_e32 v30, v77, v34
	v_exp_f32_e32 v30, v30
	v_sub_f32_e32 v42, v56, v34
	v_exp_f32_e32 v86, v42
	v_sub_f32_e32 v42, v58, v34
	v_add_f32_e32 v37, v30, v31
	v_sub_f32_e32 v31, v78, v34
	v_exp_f32_e32 v31, v31
	v_exp_f32_e32 v89, v42
	v_sub_f32_e32 v42, v60, v34
	v_exp_f32_e32 v91, v42
	v_add_f32_e32 v38, v31, v37
	v_sub_f32_e32 v37, v48, v34
	v_exp_f32_e32 v37, v37
	v_sub_f32_e32 v42, v61, v34
	v_exp_f32_e32 v106, v42
	v_exp_f32_e32 v48, v1
	v_add_f32_e32 v39, v37, v38
	v_sub_f32_e32 v38, v49, v34
	v_exp_f32_e32 v38, v38
	v_sub_f32_e32 v1, v2, v34
	v_exp_f32_e32 v49, v1
	v_sub_f32_e32 v1, v3, v34
	v_add_f32_e32 v40, v38, v39
	v_sub_f32_e32 v39, v79, v34
	v_exp_f32_e32 v39, v39
	v_exp_f32_e32 v52, v1
	v_sub_f32_e32 v1, v4, v34
	v_exp_f32_e32 v53, v1
	v_add_f32_e32 v40, v39, v40
	v_add_f32_e32 v40, v41, v40
	v_add_f32_e32 v40, v44, v40
	v_add_f32_e32 v40, v50, v40
	v_add_f32_e32 v40, v55, v40
	v_add_f32_e32 v40, v65, v40
	v_add_f32_e32 v40, v68, v40
	v_add_f32_e32 v40, v73, v40
	v_add_f32_e32 v40, v76, v40
	v_add_f32_e32 v40, v81, v40
	v_add_f32_e32 v40, v86, v40
	v_add_f32_e32 v40, v89, v40
	v_add_f32_e32 v40, v91, v40
	v_add_f32_e32 v42, v106, v40
	v_exp_f32_e32 v40, v32
	v_sub_f32_e32 v1, v5, v34
	v_exp_f32_e32 v56, v1
	v_sub_f32_e32 v1, v6, v34
	v_add_f32_e32 v32, v40, v42
	v_exp_f32_e32 v42, v33
	v_sub_f32_e32 v33, v62, v34
	v_exp_f32_e32 v43, v33
	v_sub_f32_e32 v33, v63, v34
	v_exp_f32_e32 v47, v33
	v_sub_f32_e32 v33, v35, v34
	v_exp_f32_e32 v62, v33
	v_sub_f32_e32 v33, v36, v34
	v_add_f32_e32 v32, v42, v32
	v_exp_f32_e32 v70, v33
	v_sub_f32_e32 v33, v88, v34
	v_add_f32_e32 v32, v43, v32
	v_exp_f32_e32 v74, v33
	v_sub_f32_e32 v33, v105, v34
	v_add_f32_e32 v32, v47, v32
	v_exp_f32_e32 v77, v33
	v_sub_f32_e32 v33, v87, v34
	v_add_f32_e32 v32, v62, v32
	v_exp_f32_e32 v78, v33
	v_sub_f32_e32 v33, v90, v34
	v_add_f32_e32 v32, v70, v32
	v_exp_f32_e32 v82, v33
	v_sub_f32_e32 v33, v108, v34
	v_add_f32_e32 v32, v74, v32
	v_exp_f32_e32 v84, v33
	v_sub_f32_e32 v33, v109, v34
	v_add_f32_e32 v32, v77, v32
	v_exp_f32_e32 v88, v33
	v_sub_f32_e32 v33, v107, v34
	v_add_f32_e32 v32, v78, v32
	v_exp_f32_e32 v105, v33
	v_sub_f32_e32 v33, v45, v34
	v_add_f32_e32 v32, v82, v32
	v_exp_f32_e32 v108, v33
	v_sub_f32_e32 v33, v110, v34
	v_add_f32_e32 v32, v84, v32
	v_exp_f32_e32 v109, v33
	v_sub_f32_e32 v33, v111, v34
	v_add_f32_e32 v32, v88, v32
	v_exp_f32_e32 v111, v33
	v_sub_f32_e32 v33, v46, v34
	v_add_f32_e32 v32, v105, v32
	v_exp_f32_e32 v46, v33
	v_sub_f32_e32 v33, v104, v34
	v_add_f32_e32 v32, v108, v32
	v_exp_f32_e32 v51, v33
	v_sub_f32_e32 v33, v113, v34
	v_add_f32_e32 v32, v109, v32
	v_exp_f32_e32 v58, v33
	v_sub_f32_e32 v33, v115, v34
	v_add_f32_e32 v32, v111, v32
	v_exp_f32_e32 v67, v33
	v_sub_f32_e32 v33, v112, v34
	v_add_f32_e32 v32, v46, v32
	v_exp_f32_e32 v75, v33
	v_sub_f32_e32 v33, v114, v34
	v_add_f32_e32 v32, v51, v32
	v_exp_f32_e32 v79, v33
	v_sub_f32_e32 v33, v117, v34
	v_add_f32_e32 v32, v58, v32
	v_exp_f32_e32 v83, v33
	v_sub_f32_e32 v33, v119, v34
	v_add_f32_e32 v32, v67, v32
	v_exp_f32_e32 v85, v33
	v_sub_f32_e32 v33, v116, v34
	v_add_f32_e32 v32, v75, v32
	v_exp_f32_e32 v87, v33
	v_sub_f32_e32 v33, v118, v34
	v_add_f32_e32 v32, v79, v32
	v_exp_f32_e32 v90, v33
	v_sub_f32_e32 v33, v121, v34
	v_add_f32_e32 v32, v83, v32
	v_exp_f32_e32 v104, v33
	v_sub_f32_e32 v33, v123, v34
	v_add_f32_e32 v32, v85, v32
	v_exp_f32_e32 v107, v33
	v_sub_f32_e32 v33, v120, v34
	v_add_f32_e32 v32, v87, v32
	v_exp_f32_e32 v110, v33
	v_sub_f32_e32 v33, v122, v34
	v_add_f32_e32 v32, v90, v32
	v_exp_f32_e32 v112, v33
	v_sub_f32_e32 v33, v124, v34
	v_add_f32_e32 v32, v104, v32
	v_exp_f32_e32 v113, v33
	v_sub_f32_e32 v33, v125, v34
	v_add_f32_e32 v32, v107, v32
	v_exp_f32_e32 v114, v33
	v_add_f32_e32 v32, v110, v32
	v_exp_f32_e32 v45, v0
; __device__ __forceinline__ float shfl_idx(float v, int srclane) { return __int_as_float(__builtin_amdgcn_ds_bpermute(srclane << 2, __float_as_int(v))); }
; #define SBAR() __builtin_amdgcn_sched_barrier(0)
; __device__ __forceinline__ int v_st2(int k, int c) { const int kk = (k & ~0xC) | ((k & 4) << 1) | ((k & 8) >> 1); return ((kk >> 3) * 2 + (c >> 5)) * 512 + ((kk & 7) * 32 + (c & 31)) * 2; }
; __device__ __forceinline__ int v_rd_base(int lane) { return ((lane & 3) << 3) | (((lane >> 2) & 3) << 6) | (((lane >> 4) & 1) << 5) | (((lane >> 5) & 1) << 8); }
; __device__ __forceinline__ void dil_wave_item(const bf16* __restrict__ qkv, bf16* __restrict__ odil, float* __restrict__ lse,
;                               int pat, int g  , int head, char* wl  , const int W) {
;     ...
;     for (int r = 0; r < 16; ++r) { const float e = __builtin_amdgcn_exp2f(sc[kb][r] - mx); sc[kb][r] = e; ls += e; }
;   ls += shfl_idx(ls, lane ^ 32);
;   f32x16 o0 = {}, o1 = {};
;   const int vb = (int)(uintptr_t)wl + v_rd_base(lane);
; #pragma unroll
;   for (int kb = 0; kb < 5; ++kb) {
;     bf16x8 vr[4];
; #pragma unroll
;     for (int i = 0; i < 4; ++i) {
;       const int key = i * 8 + (lane >> 3);
;       int kc = i0 - 64 + kb * 32 + key; kc = min(max(kc, 0), L - 1);
;       vr[i] = *reinterpret_cast<const bf16x8*>(qkv + (size_t)(tbase + kc * dil) * LDQ + 2560 + head * 64 + (lane & 7) * 8);
;     }
; #pragma unroll
;     for (int i = 0; i < 4; ++i) *reinterpret_cast<bf16x8*>(wl + v_st2(i * 8 + (lane >> 3), (lane & 7) * 8)) = vr[i];
;     bf16x8 pa0, pa1;
;     PK4(sc[kb], 0, pa0); PK4(sc[kb], 8, pa1);
;     asm volatile("s_waitcnt lgkmcnt(0)" ::: "memory");
;     const s16x4 a0 = tr_read<v_rd_off2(0, 0, 0)>(vb), b0 = tr_read<v_rd_off2(0, 0, 1)>(vb), a1 = tr_read<v_rd_off2(0, 1, 0)>(vb), b1 = tr_read<v_rd_off2(0, 1, 1)>(vb);
;     const s16x4 c0 = tr_read<v_rd_off2(1, 0, 0)>(vb), d0_ = tr_read<v_rd_off2(1, 0, 1)>(vb), c1 = tr_read<v_rd_off2(1, 1, 0)>(vb), d1 = tr_read<v_rd_off2(1, 1, 1)>(vb);
;     asm volatile("s_waitcnt lgkmcnt(0)" ::: "memory"); SBAR();
;     o0 = __builtin_amdgcn_mfma_f32_32x32x16_bf16(pa0, PKV(a0, b0), o0, 0, 0, 0);
;     o0 = __builtin_amdgcn_mfma_f32_32x32x16_bf16(pa1, PKV(a1, b1), o0, 0, 0, 0);
;     o1 = __builtin_amdgcn_mfma_f32_32x32x16_bf16(pa0, PKV(c0, d0_), o1, 0, 0, 0);
;     o1 = __builtin_amdgcn_mfma_f32_32x32x16_bf16(pa1, PKV(c1, d1), o1, 0, 0, 0);
	v_add_f32_e32 v32, v112, v32
	v_add_f32_e32 v32, v113, v32
	v_add_f32_e32 v32, v114, v32
	v_add_f32_e32 v0, v45, v32
	v_add_f32_e32 v0, v48, v0
	v_add_f32_e32 v0, v49, v0
	v_exp_f32_e32 v59, v1
	v_sub_f32_e32 v1, v7, v34
	v_add_f32_e32 v0, v52, v0
	v_exp_f32_e32 v63, v1
	v_sub_f32_e32 v1, v8, v34
	v_add_f32_e32 v0, v53, v0
	v_exp_f32_e32 v54, v1
	v_sub_f32_e32 v1, v9, v34
	v_add_f32_e32 v0, v56, v0
	v_exp_f32_e32 v57, v1
	v_sub_f32_e32 v1, v10, v34
	v_add_f32_e32 v0, v59, v0
	v_exp_f32_e32 v60, v1
	v_sub_f32_e32 v1, v11, v34
	v_add_f32_e32 v0, v63, v0
	v_exp_f32_e32 v64, v1
	v_sub_f32_e32 v1, v12, v34
	v_add_f32_e32 v0, v54, v0
	v_exp_f32_e32 v66, v1
	v_sub_f32_e32 v1, v13, v34
	v_add_f32_e32 v0, v57, v0
	v_exp_f32_e32 v69, v1
	v_sub_f32_e32 v1, v14, v34
	v_add_f32_e32 v0, v60, v0
	v_exp_f32_e32 v71, v1
	v_sub_f32_e32 v1, v15, v34
	v_add_f32_e32 v0, v64, v0
	v_exp_f32_e32 v72, v1
	v_add_f32_e32 v0, v66, v0
	v_add_f32_e32 v0, v69, v0
	v_add_f32_e32 v0, v71, v0
	v_lshlrev_b32_e32 v1, 4, v103
	v_add_f32_e32 v35, v72, v0
	v_lshlrev_b32_e32 v0, 3, v99
	v_and_b32_e32 v2, 0xc0, v1
	v_lshlrev_b32_e32 v3, 1, v103
	v_and_or_b32 v2, v0, 24, v2
	v_and_b32_e32 v3, 32, v3
	v_and_b32_e32 v0, 0x100, v0
	v_bfe_u32 v116, v103, 3, 3
	v_or3_b32 v0, v2, v3, v0
	v_or_b32_e32 v12, s41, v116
	v_add_u32_e32 v61, s55, v0
	v_subrev_u32_e32 v115, 64, v12
	v_lshlrev_b32_e32 v0, 3, v103
	v_and_b32_e32 v2, 56, v0
	v_bfe_u32 v117, v0, 5, 1
	v_max_i32_e32 v0, 0, v115
	v_min_u32_e32 v0, s15, v0
	v_subrev_u32_e32 v4, 56, v12
	v_lshlrev_b32_e32 v0, s40, v0
	v_max_i32_e32 v4, 0, v4
	v_add_u32_e32 v0, s42, v0
	v_min_u32_e32 v4, s15, v4
	v_subrev_u32_e32 v8, 48, v12
	v_and_b32_e32 v118, 48, v1
	v_mad_i64_i32 v[0:1], s[6:7], v0, s24, v[96:97]
	v_lshlrev_b32_e32 v4, s40, v4
	v_max_i32_e32 v8, 0, v8
	v_lshl_add_u64 v[0:1], v[0:1], 0, s[74:75]
	v_lshlrev_b32_e32 v32, 1, v2
	v_mov_b32_e32 v33, v95
	v_add_u32_e32 v4, s42, v4
	v_min_u32_e32 v8, s15, v8
	v_subrev_u32_e32 v12, 40, v12
	v_lshl_add_u64 v[0:1], v[0:1], 0, v[32:33]
	v_mad_i64_i32 v[4:5], s[6:7], v4, s24, v[96:97]
	v_lshlrev_b32_e32 v8, s40, v8
	v_max_i32_e32 v12, 0, v12
	v_add_co_u32_e32 v0, vcc, s25, v0
	v_lshl_add_u64 v[4:5], v[4:5], 0, s[74:75]
	v_add_u32_e32 v8, s42, v8
	v_min_u32_e32 v12, s15, v12
	v_addc_co_u32_e32 v1, vcc, 0, v1, vcc
	v_lshl_add_u64 v[4:5], v[4:5], 0, v[32:33]
	v_mad_i64_i32 v[8:9], s[6:7], v8, s24, v[96:97]
	v_lshlrev_b32_e32 v12, s40, v12
	v_add_co_u32_e32 v4, vcc, s25, v4
	v_lshl_add_u64 v[8:9], v[8:9], 0, s[74:75]
	v_add_u32_e32 v12, s42, v12
	v_addc_co_u32_e32 v5, vcc, 0, v5, vcc
	v_lshl_add_u64 v[8:9], v[8:9], 0, v[32:33]
	v_mad_i64_i32 v[12:13], s[6:7], v12, s24, v[96:97]
	global_load_dwordx4 v[0:3], v[0:1], off offset:1024
	v_add_co_u32_e32 v8, vcc, s25, v8
	v_lshl_add_u64 v[12:13], v[12:13], 0, s[74:75]
	s_nop 0
	v_addc_co_u32_e32 v9, vcc, 0, v9, vcc
	v_lshl_add_u64 v[12:13], v[12:13], 0, v[32:33]
	global_load_dwordx4 v[4:7], v[4:5], off offset:1024
	v_add_co_u32_e32 v12, vcc, s25, v12
	global_load_dwordx4 v[8:11], v[8:9], off offset:1024
	s_nop 0
	v_addc_co_u32_e32 v13, vcc, 0, v13, vcc
	global_load_dwordx4 v[12:15], v[12:13], off offset:1024
	v_lshrrev_b32_e32 v103, 4, v103
	v_and_or_b32 v103, v103, 2, v117
	v_lshlrev_b32_e32 v116, 6, v116
	s_movk_i32 s6, 0xc0
	v_and_or_b32 v117, v116, s6, v118
	v_lshl_add_u32 v103, v103, 9, s55
	v_add_u32_e32 v140, v103, v117
	s_movk_i32 s6, 0x100
	ds_bpermute_b32 v36, v126, v35
	s_waitcnt vmcnt(3)
	ds_write_b128 v140, v[0:3]
	v_or3_b32 v0, v116, v118, s6
	v_add_u32_e32 v103, v103, v0
	s_waitcnt vmcnt(2)
	ds_write_b128 v103, v[4:7]
	s_waitcnt vmcnt(1)
	ds_write_b128 v140, v[8:11] offset:2048
	s_waitcnt vmcnt(0)
	ds_write_b128 v103, v[12:15] offset:2048
	v_cvt_pk_bf16_f32 v16, v16, v17
	v_cvt_pk_bf16_f32 v17, v18, v19
	v_cvt_pk_bf16_f32 v18, v20, v21
	v_cvt_pk_bf16_f32 v19, v22, v23
	v_cvt_pk_bf16_f32 v116, v24, v25
	v_cvt_pk_bf16_f32 v117, v26, v27
	v_cvt_pk_bf16_f32 v118, v28, v29
	v_cvt_pk_bf16_f32 v119, v30, v31
	s_waitcnt lgkmcnt(0)
	ds_read_b64_tr_b16 v[0:1], v61 offset:0
	ds_read_b64_tr_b16 v[2:3], v61 offset:0x400
	ds_read_b64_tr_b16 v[20:21], v61 offset:0x800
	ds_read_b64_tr_b16 v[22:23], v61 offset:0xc00
	ds_read_b64_tr_b16 v[24:25], v61 offset:0x200
	ds_read_b64_tr_b16 v[26:27], v61 offset:0x600
	ds_read_b64_tr_b16 v[120:121], v61 offset:0xa00
	ds_read_b64_tr_b16 v[122:123], v61 offset:0xe00
	s_waitcnt lgkmcnt(0)
	s_nop 0
	v_permlane32_swap_b32_e32 v16, v18
	v_permlane32_swap_b32_e32 v17, v19
	v_permlane32_swap_b32_e32 v116, v118
	v_permlane32_swap_b32_e32 v117, v119
	v_mfma_f32_32x32x16_bf16 v[0:15], v[0:3], v[16:19], 0
	s_nop 0
	v_mfma_f32_32x32x16_bf16 v[0:15], v[20:23], v[116:119], v[0:15]
	v_mfma_f32_32x32x16_bf16 v[16:31], v[24:27], v[16:19], 0
	v_mfma_f32_32x32x16_bf16 v[16:31], v[120:123], v[116:119], v[16:31]
	v_max_i32_e32 v116, 0xffffffe0, v115
	v_add_u32_e32 v116, 32, v116
	v_min_u32_e32 v116, s15, v116
	v_max_i32_e32 v118, 0xffffffd8, v115
	v_lshlrev_b32_e32 v116, s40, v116
	v_add_u32_e32 v118, 40, v118
	v_add_u32_e32 v116, s42, v116
	v_min_u32_e32 v118, s15, v118
	v_max_i32_e32 v124, 0xffffffd0, v115
	v_mad_i64_i32 v[116:117], s[6:7], v116, s24, v[96:97]
	v_lshlrev_b32_e32 v118, s40, v118
	v_add_u32_e32 v124, 48, v124
	v_lshl_add_u64 v[116:117], v[116:117], 0, s[74:75]
	v_add_u32_e32 v118, s42, v118
	v_min_u32_e32 v124, s15, v124
	v_max_i32_e32 v126, 0xffffffc8, v115
	v_lshl_add_u64 v[116:117], v[116:117], 0, v[32:33]
	v_mad_i64_i32 v[118:119], s[6:7], v118, s24, v[96:97]
	v_lshlrev_b32_e32 v124, s40, v124
	v_add_u32_e32 v126, 56, v126
	v_add_co_u32_e32 v116, vcc, s25, v116
	v_lshl_add_u64 v[118:119], v[118:119], 0, s[74:75]
	v_add_u32_e32 v124, s42, v124
	v_min_u32_e32 v126, s15, v126
	v_addc_co_u32_e32 v117, vcc, 0, v117, vcc
	v_lshl_add_u64 v[118:119], v[118:119], 0, v[32:33]
	v_mad_i64_i32 v[124:125], s[6:7], v124, s24, v[96:97]
	v_lshlrev_b32_e32 v126, s40, v126
	v_add_co_u32_e32 v120, vcc, s25, v118
	v_lshl_add_u64 v[124:125], v[124:125], 0, s[74:75]
	v_add_u32_e32 v126, s42, v126
	v_addc_co_u32_e32 v121, vcc, 0, v119, vcc
	v_lshl_add_u64 v[124:125], v[124:125], 0, v[32:33]
	v_mad_i64_i32 v[126:127], s[6:7], v126, s24, v[96:97]
	v_add_co_u32_e32 v124, vcc, s25, v124
	v_lshl_add_u64 v[126:127], v[126:127], 0, s[74:75]
	s_nop 0
	v_addc_co_u32_e32 v125, vcc, 0, v125, vcc
	v_lshl_add_u64 v[126:127], v[126:127], 0, v[32:33]
	v_add_co_u32_e32 v128, vcc, s25, v126
	global_load_dwordx4 v[116:119], v[116:117], off offset:1024
	s_nop 0
	global_load_dwordx4 v[120:123], v[120:121], off offset:1024
	v_addc_co_u32_e32 v129, vcc, 0, v127, vcc
	global_load_dwordx4 v[124:127], v[124:125], off offset:1024
	s_nop 0
	global_load_dwordx4 v[128:131], v[128:129], off offset:1024
	s_waitcnt vmcnt(3)
; #define SBAR() __builtin_amdgcn_sched_barrier(0)
; __device__ __forceinline__ int v_st2(int k, int c) { const int kk = (k & ~0xC) | ((k & 4) << 1) | ((k & 8) >> 1); return ((kk >> 3) * 2 + (c >> 5)) * 512 + ((kk & 7) * 32 + (c & 31)) * 2; }
; __device__ __forceinline__ void dil_wave_item(const bf16* __restrict__ qkv, bf16* __restrict__ odil, float* __restrict__ lse,
;                               int pat, int g  , int head, char* wl  , const int W) {
;     ...
; #pragma unroll
;   for (int kb = 0; kb < 5; ++kb) {
;     bf16x8 vr[4];
; #pragma unroll
;     for (int i = 0; i < 4; ++i) {
;       const int key = i * 8 + (lane >> 3);
;       int kc = i0 - 64 + kb * 32 + key; kc = min(max(kc, 0), L - 1);
;       vr[i] = *reinterpret_cast<const bf16x8*>(qkv + (size_t)(tbase + kc * dil) * LDQ + 2560 + head * 64 + (lane & 7) * 8);
;     }
; #pragma unroll
;     for (int i = 0; i < 4; ++i) *reinterpret_cast<bf16x8*>(wl + v_st2(i * 8 + (lane >> 3), (lane & 7) * 8)) = vr[i];
;     bf16x8 pa0, pa1;
;     PK4(sc[kb], 0, pa0); PK4(sc[kb], 8, pa1);
;     asm volatile("s_waitcnt lgkmcnt(0)" ::: "memory");
;     const s16x4 a0 = tr_read<v_rd_off2(0, 0, 0)>(vb), b0 = tr_read<v_rd_off2(0, 0, 1)>(vb), a1 = tr_read<v_rd_off2(0, 1, 0)>(vb), b1 = tr_read<v_rd_off2(0, 1, 1)>(vb);
;     const s16x4 c0 = tr_read<v_rd_off2(1, 0, 0)>(vb), d0_ = tr_read<v_rd_off2(1, 0, 1)>(vb), c1 = tr_read<v_rd_off2(1, 1, 0)>(vb), d1 = tr_read<v_rd_off2(1, 1, 1)>(vb);
;     asm volatile("s_waitcnt lgkmcnt(0)" ::: "memory"); SBAR();
;     o0 = __builtin_amdgcn_mfma_f32_32x32x16_bf16(pa0, PKV(a0, b0), o0, 0, 0, 0);
;     o0 = __builtin_amdgcn_mfma_f32_32x32x16_bf16(pa1, PKV(a1, b1), o0, 0, 0, 0);
;     o1 = __builtin_amdgcn_mfma_f32_32x32x16_bf16(pa0, PKV(c0, d0_), o1, 0, 0, 0);
;     o1 = __builtin_amdgcn_mfma_f32_32x32x16_bf16(pa1, PKV(c1, d1), o1, 0, 0, 0);
	ds_write_b128 v140, v[116:119]
	s_waitcnt vmcnt(2)
	ds_write_b128 v103, v[120:123]
	s_waitcnt vmcnt(1)
	ds_write_b128 v140, v[124:127] offset:2048
	s_waitcnt vmcnt(0)
	ds_write_b128 v103, v[128:131] offset:2048
	v_cvt_pk_bf16_f32 v116, v37, v38
	v_cvt_pk_bf16_f32 v117, v39, v41
	v_cvt_pk_bf16_f32 v118, v44, v50
	v_cvt_pk_bf16_f32 v119, v55, v65
	v_cvt_pk_bf16_f32 v120, v68, v73
	v_cvt_pk_bf16_f32 v121, v76, v81
	v_cvt_pk_bf16_f32 v122, v86, v89
	v_cvt_pk_bf16_f32 v123, v91, v106
	s_waitcnt lgkmcnt(0)
	ds_read_b64_tr_b16 v[124:125], v61 offset:0
	ds_read_b64_tr_b16 v[126:127], v61 offset:0x400
	ds_read_b64_tr_b16 v[128:129], v61 offset:0x800
	ds_read_b64_tr_b16 v[130:131], v61 offset:0xc00
	ds_read_b64_tr_b16 v[132:133], v61 offset:0x200
	ds_read_b64_tr_b16 v[134:135], v61 offset:0x600
	ds_read_b64_tr_b16 v[136:137], v61 offset:0xa00
	ds_read_b64_tr_b16 v[138:139], v61 offset:0xe00
	s_waitcnt lgkmcnt(0)
	s_nop 0
	v_permlane32_swap_b32_e32 v116, v118
	v_permlane32_swap_b32_e32 v117, v119
	v_permlane32_swap_b32_e32 v120, v122
	v_permlane32_swap_b32_e32 v121, v123
	v_mfma_f32_32x32x16_bf16 v[0:15], v[124:127], v[116:119], v[0:15]
	v_mfma_f32_32x32x16_bf16 v[16:31], v[132:135], v[116:119], v[16:31]
	v_mfma_f32_32x32x16_bf16 v[0:15], v[128:131], v[120:123], v[0:15]
	v_mfma_f32_32x32x16_bf16 v[16:31], v[136:139], v[120:123], v[16:31]
	v_max_i32_e32 v37, 0xffffffc0, v115
	v_add_u32_e32 v37, 64, v37
	v_min_u32_e32 v37, s15, v37
	v_lshlrev_b32_e32 v37, s40, v37
	v_add_u32_e32 v37, s42, v37
	v_mad_i64_i32 v[38:39], s[6:7], v37, s24, v[96:97]
	v_max_i32_e32 v37, 0xffffffb8, v115
	v_add_u32_e32 v37, 0x48, v37
	v_min_u32_e32 v37, s15, v37
	v_lshlrev_b32_e32 v37, s40, v37
	v_lshl_add_u64 v[38:39], v[38:39], 0, s[74:75]
	v_add_u32_e32 v37, s42, v37
	v_lshl_add_u64 v[38:39], v[38:39], 0, v[32:33]
	v_mad_i64_i32 v[116:117], s[6:7], v37, s24, v[96:97]
	v_max_i32_e32 v37, 0xffffffb0, v115
	v_add_co_u32_e32 v38, vcc, s25, v38
	v_lshl_add_u64 v[116:117], v[116:117], 0, s[74:75]
	v_add_u32_e32 v37, 0x50, v37
	v_addc_co_u32_e32 v39, vcc, 0, v39, vcc
	v_lshl_add_u64 v[116:117], v[116:117], 0, v[32:33]
	v_min_u32_e32 v37, s15, v37
	v_add_co_u32_e32 v120, vcc, s25, v116
	v_lshlrev_b32_e32 v37, s40, v37
	s_nop 0
	v_addc_co_u32_e32 v121, vcc, 0, v117, vcc
	v_add_u32_e32 v37, s42, v37
	global_load_dwordx4 v[116:119], v[38:39], off offset:1024
	s_nop 0
	global_load_dwordx4 v[120:123], v[120:121], off offset:1024
	v_mad_i64_i32 v[38:39], s[6:7], v37, s24, v[96:97]
	v_max_i32_e32 v37, 0xffffffa8, v115
	v_add_u32_e32 v37, 0x58, v37
	v_min_u32_e32 v37, s15, v37
	v_lshlrev_b32_e32 v37, s40, v37
	v_lshl_add_u64 v[38:39], v[38:39], 0, s[74:75]
	v_add_u32_e32 v37, s42, v37
	v_lshl_add_u64 v[38:39], v[38:39], 0, v[32:33]
	v_mad_i64_i32 v[124:125], s[6:7], v37, s24, v[96:97]
	v_add_co_u32_e32 v38, vcc, s25, v38
	v_lshl_add_u64 v[124:125], v[124:125], 0, s[74:75]
	s_nop 0
	v_addc_co_u32_e32 v39, vcc, 0, v39, vcc
	v_lshl_add_u64 v[124:125], v[124:125], 0, v[32:33]
	v_add_co_u32_e32 v128, vcc, s25, v124
	s_nop 1
	v_addc_co_u32_e32 v129, vcc, 0, v125, vcc
	global_load_dwordx4 v[124:127], v[38:39], off offset:1024
	s_nop 0
	global_load_dwordx4 v[128:131], v[128:129], off offset:1024
	s_waitcnt vmcnt(3)
	ds_write_b128 v140, v[116:119]
	s_waitcnt vmcnt(2)
	ds_write_b128 v103, v[120:123]
	s_waitcnt vmcnt(1)
	ds_write_b128 v140, v[124:127] offset:2048
	s_waitcnt vmcnt(0)
	ds_write_b128 v103, v[128:131] offset:2048
	v_cvt_pk_bf16_f32 v38, v40, v42
	v_cvt_pk_bf16_f32 v39, v43, v47
	v_cvt_pk_bf16_f32 v40, v62, v70
	v_cvt_pk_bf16_f32 v41, v74, v77
	v_cvt_pk_bf16_f32 v116, v78, v82
	v_cvt_pk_bf16_f32 v117, v84, v88
	v_cvt_pk_bf16_f32 v118, v105, v108
	v_cvt_pk_bf16_f32 v119, v109, v111
	s_waitcnt lgkmcnt(0)
	ds_read_b64_tr_b16 v[120:121], v61 offset:0
	ds_read_b64_tr_b16 v[122:123], v61 offset:0x400
	ds_read_b64_tr_b16 v[124:125], v61 offset:0x800
	ds_read_b64_tr_b16 v[126:127], v61 offset:0xc00
	ds_read_b64_tr_b16 v[128:129], v61 offset:0x200
	ds_read_b64_tr_b16 v[130:131], v61 offset:0x600
	ds_read_b64_tr_b16 v[132:133], v61 offset:0xa00
	ds_read_b64_tr_b16 v[134:135], v61 offset:0xe00
	s_waitcnt lgkmcnt(0)
	s_nop 0
	v_permlane32_swap_b32_e32 v38, v40
	v_permlane32_swap_b32_e32 v39, v41
	v_permlane32_swap_b32_e32 v116, v118
	v_permlane32_swap_b32_e32 v117, v119
	v_mfma_f32_32x32x16_bf16 v[0:15], v[120:123], v[38:41], v[0:15]
	v_mfma_f32_32x32x16_bf16 v[16:31], v[128:131], v[38:41], v[16:31]
	v_mfma_f32_32x32x16_bf16 v[0:15], v[124:127], v[116:119], v[0:15]
	v_mfma_f32_32x32x16_bf16 v[16:31], v[132:135], v[116:119], v[16:31]
	v_max_i32_e32 v37, 0xffffffa0, v115
	v_add_u32_e32 v37, 0x60, v37
	v_min_u32_e32 v37, s15, v37
	v_lshlrev_b32_e32 v37, s40, v37
	v_add_u32_e32 v37, s42, v37
	v_mad_i64_i32 v[38:39], s[6:7], v37, s24, v[96:97]
	v_max_i32_e32 v37, 0xffffff98, v115
	v_add_u32_e32 v37, 0x68, v37
	v_min_u32_e32 v37, s15, v37
	v_lshlrev_b32_e32 v37, s40, v37
	v_lshl_add_u64 v[38:39], v[38:39], 0, s[74:75]
	v_add_u32_e32 v37, s42, v37
	v_lshl_add_u64 v[38:39], v[38:39], 0, v[32:33]
	v_mad_i64_i32 v[40:41], s[6:7], v37, s24, v[96:97]
	v_max_i32_e32 v37, 0xffffff90, v115
	v_add_co_u32_e32 v38, vcc, s25, v38
	v_lshl_add_u64 v[40:41], v[40:41], 0, s[74:75]
	v_add_u32_e32 v37, 0x70, v37
	v_addc_co_u32_e32 v39, vcc, 0, v39, vcc
	v_lshl_add_u64 v[40:41], v[40:41], 0, v[32:33]
	v_min_u32_e32 v37, s15, v37
	v_add_co_u32_e32 v42, vcc, s25, v40
	v_lshlrev_b32_e32 v37, s40, v37
	s_nop 0
	v_addc_co_u32_e32 v43, vcc, 0, v41, vcc
	v_add_u32_e32 v37, s42, v37
	global_load_dwordx4 v[38:41], v[38:39], off offset:1024
	s_nop 0
	global_load_dwordx4 v[116:119], v[42:43], off offset:1024
	v_mad_i64_i32 v[42:43], s[6:7], v37, s24, v[96:97]
	v_max_i32_e32 v37, 0xffffff88, v115
	v_add_u32_e32 v37, 0x78, v37
	v_min_u32_e32 v37, s15, v37
	v_lshlrev_b32_e32 v37, s40, v37
	v_lshl_add_u64 v[42:43], v[42:43], 0, s[74:75]
	v_add_u32_e32 v37, s42, v37
	v_lshl_add_u64 v[42:43], v[42:43], 0, v[32:33]
	v_mad_i64_i32 v[76:77], s[6:7], v37, s24, v[96:97]
	v_add_co_u32_e32 v42, vcc, s25, v42
	v_lshl_add_u64 v[76:77], v[76:77], 0, s[74:75]
	s_nop 0
	v_addc_co_u32_e32 v43, vcc, 0, v43, vcc
	v_lshl_add_u64 v[76:77], v[76:77], 0, v[32:33]
	v_add_co_u32_e32 v76, vcc, s25, v76
	s_nop 1
	v_addc_co_u32_e32 v77, vcc, 0, v77, vcc
	global_load_dwordx4 v[120:123], v[42:43], off offset:1024
	global_load_dwordx4 v[124:127], v[76:77], off offset:1024
	s_waitcnt vmcnt(3)
; #define SBAR() __builtin_amdgcn_sched_barrier(0)
; __device__ __forceinline__ int v_st2(int k, int c) { const int kk = (k & ~0xC) | ((k & 4) << 1) | ((k & 8) >> 1); return ((kk >> 3) * 2 + (c >> 5)) * 512 + ((kk & 7) * 32 + (c & 31)) * 2; }
; __device__ __forceinline__ void dil_wave_item(const bf16* __restrict__ qkv, bf16* __restrict__ odil, float* __restrict__ lse,
;                               int pat, int g  , int head, char* wl  , const int W) {
;     ...
; #pragma unroll
;   for (int kb = 0; kb < 5; ++kb) {
;     bf16x8 vr[4];
; #pragma unroll
;     for (int i = 0; i < 4; ++i) {
;       const int key = i * 8 + (lane >> 3);
;       int kc = i0 - 64 + kb * 32 + key; kc = min(max(kc, 0), L - 1);
;       vr[i] = *reinterpret_cast<const bf16x8*>(qkv + (size_t)(tbase + kc * dil) * LDQ + 2560 + head * 64 + (lane & 7) * 8);
;     }
; #pragma unroll
;     for (int i = 0; i < 4; ++i) *reinterpret_cast<bf16x8*>(wl + v_st2(i * 8 + (lane >> 3), (lane & 7) * 8)) = vr[i];
;     bf16x8 pa0, pa1;
;     PK4(sc[kb], 0, pa0); PK4(sc[kb], 8, pa1);
;     asm volatile("s_waitcnt lgkmcnt(0)" ::: "memory");
;     const s16x4 a0 = tr_read<v_rd_off2(0, 0, 0)>(vb), b0 = tr_read<v_rd_off2(0, 0, 1)>(vb), a1 = tr_read<v_rd_off2(0, 1, 0)>(vb), b1 = tr_read<v_rd_off2(0, 1, 1)>(vb);
;     const s16x4 c0 = tr_read<v_rd_off2(1, 0, 0)>(vb), d0_ = tr_read<v_rd_off2(1, 0, 1)>(vb), c1 = tr_read<v_rd_off2(1, 1, 0)>(vb), d1 = tr_read<v_rd_off2(1, 1, 1)>(vb);
;     asm volatile("s_waitcnt lgkmcnt(0)" ::: "memory"); SBAR();
;     o0 = __builtin_amdgcn_mfma_f32_32x32x16_bf16(pa0, PKV(a0, b0), o0, 0, 0, 0);
;     o0 = __builtin_amdgcn_mfma_f32_32x32x16_bf16(pa1, PKV(a1, b1), o0, 0, 0, 0);
;     o1 = __builtin_amdgcn_mfma_f32_32x32x16_bf16(pa0, PKV(c0, d0_), o1, 0, 0, 0);
;     o1 = __builtin_amdgcn_mfma_f32_32x32x16_bf16(pa1, PKV(c1, d1), o1, 0, 0, 0);
;     SBAR();
;   }
;   if (hi == 0) lse[((size_t)pat * T + tbase + (i0 + r32) * dil) * 8 + head] = mx + __log2f(ls);
	ds_write_b128 v140, v[38:41]
	s_waitcnt vmcnt(2)
	ds_write_b128 v103, v[116:119]
	s_waitcnt vmcnt(1)
	ds_write_b128 v140, v[120:123] offset:2048
	s_waitcnt vmcnt(0)
	ds_write_b128 v103, v[124:127] offset:2048
	v_cvt_pk_bf16_f32 v38, v46, v51
	v_cvt_pk_bf16_f32 v39, v58, v67
	v_cvt_pk_bf16_f32 v40, v75, v79
	v_cvt_pk_bf16_f32 v41, v83, v85
	v_cvt_pk_bf16_f32 v74, v87, v90
	v_cvt_pk_bf16_f32 v75, v104, v107
	v_cvt_pk_bf16_f32 v76, v110, v112
	v_cvt_pk_bf16_f32 v77, v113, v114
	s_waitcnt lgkmcnt(0)
	ds_read_b64_tr_b16 v[82:83], v61 offset:0
	ds_read_b64_tr_b16 v[84:85], v61 offset:0x400
	ds_read_b64_tr_b16 v[86:87], v61 offset:0x800
	ds_read_b64_tr_b16 v[88:89], v61 offset:0xc00
	ds_read_b64_tr_b16 v[104:105], v61 offset:0x200
	ds_read_b64_tr_b16 v[106:107], v61 offset:0x600
	ds_read_b64_tr_b16 v[108:109], v61 offset:0xa00
	ds_read_b64_tr_b16 v[110:111], v61 offset:0xe00
	s_waitcnt lgkmcnt(0)
	s_nop 0
	v_permlane32_swap_b32_e32 v38, v40
	v_permlane32_swap_b32_e32 v39, v41
	v_permlane32_swap_b32_e32 v74, v76
	v_permlane32_swap_b32_e32 v75, v77
	v_mfma_f32_32x32x16_bf16 v[0:15], v[82:85], v[38:41], v[0:15]
	v_mfma_f32_32x32x16_bf16 v[16:31], v[104:107], v[38:41], v[16:31]
	v_mfma_f32_32x32x16_bf16 v[0:15], v[86:89], v[74:77], v[0:15]
	v_mfma_f32_32x32x16_bf16 v[16:31], v[108:111], v[74:77], v[16:31]
	v_max_i32_e32 v37, 0xffffff80, v115
	v_add_u32_e32 v37, 0x80, v37
	v_min_u32_e32 v37, s15, v37
	v_lshlrev_b32_e32 v37, s40, v37
	v_add_u32_e32 v37, s42, v37
	v_mad_i64_i32 v[38:39], s[6:7], v37, s24, v[96:97]
	v_max_i32_e32 v37, 0xffffff78, v115
	v_add_u32_e32 v37, 0x88, v37
	v_min_u32_e32 v37, s15, v37
	v_lshlrev_b32_e32 v37, s40, v37
	v_lshl_add_u64 v[38:39], v[38:39], 0, s[74:75]
	v_add_u32_e32 v37, s42, v37
	v_lshl_add_u64 v[38:39], v[38:39], 0, v[32:33]
	v_mad_i64_i32 v[40:41], s[6:7], v37, s24, v[96:97]
	v_max_i32_e32 v37, 0xffffff70, v115
	v_add_co_u32_e32 v38, vcc, s25, v38
	v_lshl_add_u64 v[40:41], v[40:41], 0, s[74:75]
	v_add_u32_e32 v37, 0x90, v37
	v_addc_co_u32_e32 v39, vcc, 0, v39, vcc
	v_lshl_add_u64 v[40:41], v[40:41], 0, v[32:33]
	v_min_u32_e32 v37, s15, v37
	v_add_co_u32_e32 v42, vcc, s25, v40
	v_lshlrev_b32_e32 v37, s40, v37
	s_nop 0
	v_addc_co_u32_e32 v43, vcc, 0, v41, vcc
	v_add_u32_e32 v37, s42, v37
	global_load_dwordx4 v[38:41], v[38:39], off offset:1024
	s_nop 0
	global_load_dwordx4 v[74:77], v[42:43], off offset:1024
	v_mad_i64_i32 v[42:43], s[6:7], v37, s24, v[96:97]
	v_max_i32_e32 v37, 0xffffff68, v115
	v_add_u32_e32 v37, 0x98, v37
	v_min_u32_e32 v37, s15, v37
	v_lshlrev_b32_e32 v37, s40, v37
	v_lshl_add_u64 v[42:43], v[42:43], 0, s[74:75]
	v_add_u32_e32 v37, s42, v37
	v_lshl_add_u64 v[42:43], v[42:43], 0, v[32:33]
	v_mad_i64_i32 v[46:47], s[6:7], v37, s24, v[96:97]
	v_add_co_u32_e32 v42, vcc, s25, v42
	v_lshl_add_u64 v[46:47], v[46:47], 0, s[74:75]
	s_nop 0
	v_addc_co_u32_e32 v43, vcc, 0, v43, vcc
	v_lshl_add_u64 v[32:33], v[46:47], 0, v[32:33]
	v_add_co_u32_e32 v32, vcc, s25, v32
	s_nop 1
	v_addc_co_u32_e32 v33, vcc, 0, v33, vcc
	global_load_dwordx4 v[82:85], v[42:43], off offset:1024
	global_load_dwordx4 v[86:89], v[32:33], off offset:1024
	s_waitcnt vmcnt(3)
	ds_write_b128 v140, v[38:41]
	s_waitcnt vmcnt(2)
	ds_write_b128 v103, v[74:77]
	s_waitcnt vmcnt(1)
	ds_write_b128 v140, v[82:85] offset:2048
	s_waitcnt vmcnt(0)
	ds_write_b128 v103, v[86:89] offset:2048
	v_cvt_pk_bf16_f32 v38, v45, v48
	v_cvt_pk_bf16_f32 v39, v49, v52
	v_cvt_pk_bf16_f32 v40, v53, v56
	v_cvt_pk_bf16_f32 v41, v59, v63
	v_cvt_pk_bf16_f32 v42, v54, v57
	v_cvt_pk_bf16_f32 v43, v60, v64
	v_cvt_pk_bf16_f32 v44, v66, v69
	v_cvt_pk_bf16_f32 v45, v71, v72
	s_waitcnt lgkmcnt(0)
	ds_read_b64_tr_b16 v[46:47], v61 offset:0
	ds_read_b64_tr_b16 v[48:49], v61 offset:0x400
	ds_read_b64_tr_b16 v[50:51], v61 offset:0x800
	ds_read_b64_tr_b16 v[52:53], v61 offset:0xc00
	ds_read_b64_tr_b16 v[54:55], v61 offset:0x200
	ds_read_b64_tr_b16 v[56:57], v61 offset:0x600
	ds_read_b64_tr_b16 v[62:63], v61 offset:0xa00
	ds_read_b64_tr_b16 v[64:65], v61 offset:0xe00
	s_waitcnt lgkmcnt(0)
	s_nop 0
	v_permlane32_swap_b32_e32 v38, v40
	v_permlane32_swap_b32_e32 v39, v41
	v_permlane32_swap_b32_e32 v42, v44
	v_permlane32_swap_b32_e32 v43, v45
	v_mfma_f32_32x32x16_bf16 v[0:15], v[46:49], v[38:41], v[0:15]
	v_mfma_f32_32x32x16_bf16 v[16:31], v[54:57], v[38:41], v[16:31]
	v_mfma_f32_32x32x16_bf16 v[0:15], v[50:53], v[42:45], v[0:15]
	v_mfma_f32_32x32x16_bf16 v[16:31], v[62:65], v[42:45], v[16:31]
	v_cmp_lt_u32_e32 vcc, 31, v99
	s_and_saveexec_b64 s[6:7], vcc
	s_xor_b64 s[6:7], exec, s[6:7]
	s_ashr_i32 s15, s14, 31
	s_lshl_b64 s[8:9], s[14:15], 15
	s_ashr_i32 s15, s42, 31
	s_add_u32 s20, s8, s42
	s_addc_u32 s21, s9, s15
	s_or_saveexec_b64 s[6:7], s[6:7]
	s_waitcnt lgkmcnt(14)
	v_add_f32_e32 v35, v35, v36
	v_mov_b64_e32 v[32:33], s[20:21]
	s_xor_b64 exec, exec, s[6:7]
	s_cbranch_execz .LBB0_293
	v_log_f32_e32 v32, v35
	s_ashr_i32 s15, s14, 31
	s_lshl_b64 s[8:9], s[14:15], 15
	s_ashr_i32 s14, s42, 31
	s_add_u32 s8, s8, s42
	s_addc_u32 s9, s9, s14
	v_ashrrev_i32_e32 v99, 31, v98
	v_add_f32_e32 v34, v34, v32
	v_lshl_add_u64 v[32:33], s[8:9], 0, v[98:99]
	v_lshlrev_b64 v[32:33], 5, v[32:33]
	v_lshl_add_u64 v[32:33], s[72:73], 0, v[32:33]
	global_store_dword v[32:33], v34, off
	v_mov_b64_e32 v[32:33], s[8:9]
	s_branch .LBB0_293
